# GEMM K-loops: wave-uniform wait-select branch inverted so the common vmcnt(8) path falls through, rare vmcnt(24) path out of line
# baseline (speedup 1.0000x reference)
.LBB0_346:
	ds_read_b128 v[158:161], v153
	ds_read_b128 v[162:165], v153 offset:1024
	ds_read_b128 v[166:169], v153 offset:2048
	ds_read_b128 v[170:173], v153 offset:3072
	ds_read_b128 v[174:177], v155
	ds_read_b128 v[178:181], v155 offset:1024
	ds_read_b128 v[182:185], v155 offset:2048
	ds_read_b128 v[186:189], v155 offset:3072
	s_add_u32 s40, s30, s38
	s_addc_u32 s41, s31, s39
	s_add_u32 s42, s40, 0x100
	s_addc_u32 s43, s41, 0
	s_add_u32 s68, s25, s38
	s_addc_u32 s69, s27, s39
	s_cmp_eq_u32 s38, 0
	s_cselect_b64 s[40:41], -1, 0
	s_and_b64 s[40:41], s[36:37], s[40:41]
	s_cmpk_eq_i32 s38, 0xf00
	v_cndmask_b32_e64 v157, 0, 1, s[40:41]
	s_cselect_b32 s43, s7, s43
	s_cselect_b32 s42, s6, s42
	v_readfirstlane_b32 s70, v157
	s_cselect_b32 s41, s29, s69
	s_cselect_b32 s40, s28, s68
	v_lshl_add_u64 v[222:223], v[148:149], 0, s[38:39]
	s_add_i32 m0, s49, 0xc000
	ds_read_b128 v[190:193], v156
	ds_read_b128 v[194:197], v156 offset:1024
	ds_read_b128 v[198:201], v156 offset:2048
	ds_read_b128 v[202:205], v156 offset:3072
	ds_read_b128 v[206:209], v156 offset:4096
	ds_read_b128 v[210:213], v156 offset:5120
	ds_read_b128 v[214:217], v156 offset:6144
	ds_read_b128 v[218:221], v156 offset:7168
	global_load_lds_dwordx4 v[222:223], off
	v_lshl_add_u64 v[222:223], v[146:147], 0, s[38:39]
	s_add_i32 m0, s49, 0xe000
	s_and_b32 s70, s70, 1
	global_load_lds_dwordx4 v[222:223], off
	s_cmp_lg_u32 s70, 0
	s_cbranch_scc1 .Lgk_rare_0
	s_waitcnt vmcnt(8)
.Lgk_back_0:
	s_waitcnt lgkmcnt(0)
	s_barrier
	s_setprio 1
	s_waitcnt lgkmcnt(0)
	v_mfma_f32_16x16x32_bf16 v[126:129], v[158:161], v[190:193], v[126:129]
	v_mfma_f32_16x16x32_bf16 v[122:125], v[166:169], v[190:193], v[122:125]
	v_mfma_f32_16x16x32_bf16 v[118:121], v[158:161], v[198:201], v[118:121]
	v_mfma_f32_16x16x32_bf16 v[110:113], v[166:169], v[198:201], v[110:113]
	v_mfma_f32_16x16x32_bf16 v[102:105], v[158:161], v[206:209], v[102:105]
	v_mfma_f32_16x16x32_bf16 v[94:97], v[166:169], v[206:209], v[94:97]
	v_mfma_f32_16x16x32_bf16 v[86:89], v[158:161], v[214:217], v[86:89]
	v_mfma_f32_16x16x32_bf16 v[78:81], v[166:169], v[214:217], v[78:81]
	v_mfma_f32_16x16x32_bf16 v[126:129], v[162:165], v[194:197], v[126:129]
	v_mfma_f32_16x16x32_bf16 v[122:125], v[170:173], v[194:197], v[122:125]
	v_mfma_f32_16x16x32_bf16 v[118:121], v[162:165], v[202:205], v[118:121]
	v_mfma_f32_16x16x32_bf16 v[110:113], v[170:173], v[202:205], v[110:113]
	v_mfma_f32_16x16x32_bf16 v[102:105], v[162:165], v[210:213], v[102:105]
	v_mfma_f32_16x16x32_bf16 v[94:97], v[170:173], v[210:213], v[94:97]
	v_mfma_f32_16x16x32_bf16 v[86:89], v[162:165], v[218:221], v[86:89]
	v_mfma_f32_16x16x32_bf16 v[78:81], v[170:173], v[218:221], v[78:81]
	s_setprio 0
	s_setprio 1
	v_mfma_f32_16x16x32_bf16 v[114:117], v[174:177], v[190:193], v[114:117]
	v_mfma_f32_16x16x32_bf16 v[106:109], v[182:185], v[190:193], v[106:109]
	v_mfma_f32_16x16x32_bf16 v[98:101], v[174:177], v[198:201], v[98:101]
	v_mfma_f32_16x16x32_bf16 v[90:93], v[182:185], v[198:201], v[90:93]
	v_mfma_f32_16x16x32_bf16 v[82:85], v[174:177], v[206:209], v[82:85]
	v_mfma_f32_16x16x32_bf16 v[74:77], v[182:185], v[206:209], v[74:77]
	v_mfma_f32_16x16x32_bf16 v[70:73], v[174:177], v[214:217], v[70:73]
	v_mfma_f32_16x16x32_bf16 v[66:69], v[182:185], v[214:217], v[66:69]
	v_mfma_f32_16x16x32_bf16 v[114:117], v[178:181], v[194:197], v[114:117]
	v_mfma_f32_16x16x32_bf16 v[106:109], v[186:189], v[194:197], v[106:109]
	v_mfma_f32_16x16x32_bf16 v[98:101], v[178:181], v[202:205], v[98:101]
	v_mfma_f32_16x16x32_bf16 v[90:93], v[186:189], v[202:205], v[90:93]
	v_mfma_f32_16x16x32_bf16 v[82:85], v[178:181], v[210:213], v[82:85]
	v_mfma_f32_16x16x32_bf16 v[74:77], v[186:189], v[210:213], v[74:77]
	v_mfma_f32_16x16x32_bf16 v[70:73], v[178:181], v[218:221], v[70:73]
	v_mfma_f32_16x16x32_bf16 v[66:69], v[186:189], v[218:221], v[66:69]
	s_setprio 0
	s_barrier
	s_add_i32 s68, s58, s46
	v_lshl_add_u64 v[222:223], s[40:41], 0, v[134:135]
	s_mov_b32 m0, s68
	ds_read_b128 v[190:193], v156 offset:16384
	ds_read_b128 v[194:197], v156 offset:17408
	ds_read_b128 v[198:201], v156 offset:18432
	ds_read_b128 v[202:205], v156 offset:19456
	ds_read_b128 v[206:209], v156 offset:20480
	ds_read_b128 v[210:213], v156 offset:21504
	ds_read_b128 v[214:217], v156 offset:22528
	ds_read_b128 v[218:221], v156 offset:23552
	global_load_lds_dwordx4 v[222:223], off
	s_add_i32 m0, s68, 0x2000
	s_add_u32 s68, s40, 0x80000
	v_lshl_add_u64 v[224:225], s[40:41], 0, v[130:131]
	s_addc_u32 s69, s41, 0
	s_add_i32 s71, s59, s46
	global_load_lds_dwordx4 v[224:225], off
	v_lshl_add_u64 v[226:227], s[68:69], 0, v[134:135]
	s_mov_b32 m0, s71
	v_lshl_add_u64 v[228:229], s[42:43], 0, v[132:133]
	global_load_lds_dwordx4 v[226:227], off
	v_lshl_add_u64 v[226:227], s[68:69], 0, v[130:131]
	s_add_i32 m0, s71, 0x2000
	s_nop 0
	global_load_lds_dwordx4 v[226:227], off
	v_lshl_add_u64 v[226:227], s[42:43], 0, v[136:137]
	s_mov_b32 m0, s49
	s_nop 0
	global_load_lds_dwordx4 v[226:227], off
	s_mov_b32 m0, s50
	s_nop 0
	global_load_lds_dwordx4 v[228:229], off
	s_cmp_lg_u32 s70, 0
	s_cbranch_scc1 .Lgk_rare_1
	s_waitcnt vmcnt(8)
.Lgk_back_1:
	s_waitcnt lgkmcnt(0)
	s_barrier
	s_setprio 1
	s_waitcnt lgkmcnt(0)
	v_mfma_f32_16x16x32_bf16 v[62:65], v[158:161], v[190:193], v[62:65]
	v_mfma_f32_16x16x32_bf16 v[58:61], v[166:169], v[190:193], v[58:61]
	v_mfma_f32_16x16x32_bf16 v[54:57], v[158:161], v[198:201], v[54:57]
	v_mfma_f32_16x16x32_bf16 v[46:49], v[166:169], v[198:201], v[46:49]
	v_mfma_f32_16x16x32_bf16 v[38:41], v[158:161], v[206:209], v[38:41]
	v_mfma_f32_16x16x32_bf16 v[30:33], v[166:169], v[206:209], v[30:33]
	v_mfma_f32_16x16x32_bf16 v[22:25], v[158:161], v[214:217], v[22:25]
	v_mfma_f32_16x16x32_bf16 v[14:17], v[166:169], v[214:217], v[14:17]
	v_mfma_f32_16x16x32_bf16 v[62:65], v[162:165], v[194:197], v[62:65]
	v_mfma_f32_16x16x32_bf16 v[58:61], v[170:173], v[194:197], v[58:61]
	v_mfma_f32_16x16x32_bf16 v[54:57], v[162:165], v[202:205], v[54:57]
	v_mfma_f32_16x16x32_bf16 v[46:49], v[170:173], v[202:205], v[46:49]
	v_mfma_f32_16x16x32_bf16 v[38:41], v[162:165], v[210:213], v[38:41]
	v_mfma_f32_16x16x32_bf16 v[30:33], v[170:173], v[210:213], v[30:33]
	v_mfma_f32_16x16x32_bf16 v[22:25], v[162:165], v[218:221], v[22:25]
	v_mfma_f32_16x16x32_bf16 v[14:17], v[170:173], v[218:221], v[14:17]
	s_setprio 0
	s_setprio 1
	v_mfma_f32_16x16x32_bf16 v[50:53], v[174:177], v[190:193], v[50:53]
	v_mfma_f32_16x16x32_bf16 v[42:45], v[182:185], v[190:193], v[42:45]
	v_mfma_f32_16x16x32_bf16 v[34:37], v[174:177], v[198:201], v[34:37]
	v_mfma_f32_16x16x32_bf16 v[26:29], v[182:185], v[198:201], v[26:29]
	v_mfma_f32_16x16x32_bf16 v[18:21], v[174:177], v[206:209], v[18:21]
	v_mfma_f32_16x16x32_bf16 v[10:13], v[182:185], v[206:209], v[10:13]
	v_mfma_f32_16x16x32_bf16 v[6:9], v[174:177], v[214:217], v[6:9]
	v_mfma_f32_16x16x32_bf16 v[2:5], v[182:185], v[214:217], v[2:5]
	v_mfma_f32_16x16x32_bf16 v[50:53], v[178:181], v[194:197], v[50:53]
	v_mfma_f32_16x16x32_bf16 v[42:45], v[186:189], v[194:197], v[42:45]
	v_mfma_f32_16x16x32_bf16 v[34:37], v[178:181], v[202:205], v[34:37]
	v_mfma_f32_16x16x32_bf16 v[26:29], v[186:189], v[202:205], v[26:29]
	v_mfma_f32_16x16x32_bf16 v[18:21], v[178:181], v[210:213], v[18:21]
	v_mfma_f32_16x16x32_bf16 v[10:13], v[186:189], v[210:213], v[10:13]
	v_mfma_f32_16x16x32_bf16 v[6:9], v[178:181], v[218:221], v[6:9]
	v_mfma_f32_16x16x32_bf16 v[2:5], v[186:189], v[218:221], v[2:5]
	s_setprio 0
	s_barrier
	s_add_i32 s68, 0, 0x18000
	v_add_u32_e32 v157, s68, v150
	s_add_i32 s69, 0, 0x1c000
	ds_read_b128 v[158:161], v157
	ds_read_b128 v[162:165], v157 offset:1024
	ds_read_b128 v[166:169], v157 offset:2048
	ds_read_b128 v[170:173], v157 offset:3072
	v_add_u32_e32 v157, s69, v150
	ds_read_b128 v[174:177], v157
	ds_read_b128 v[178:181], v157 offset:1024
	ds_read_b128 v[182:185], v157 offset:2048
	ds_read_b128 v[186:189], v157 offset:3072
	s_add_u32 s42, s42, 0x80000
	s_addc_u32 s43, s43, 0
	s_mov_b32 m0, s51
	v_lshl_add_u64 v[230:231], s[42:43], 0, v[136:137]
	ds_read_b128 v[190:193], v156 offset:32768
	ds_read_b128 v[194:197], v156 offset:33792
	ds_read_b128 v[198:201], v156 offset:34816
	ds_read_b128 v[202:205], v156 offset:35840
	ds_read_b128 v[206:209], v156 offset:36864
	ds_read_b128 v[210:213], v156 offset:37888
	ds_read_b128 v[214:217], v156 offset:38912
	ds_read_b128 v[218:221], v156 offset:39936
	global_load_lds_dwordx4 v[230:231], off
	v_lshl_add_u64 v[230:231], s[42:43], 0, v[132:133]
	s_mov_b32 m0, s52
	s_nop 0
	global_load_lds_dwordx4 v[230:231], off
	s_waitcnt vmcnt(8)
	s_waitcnt lgkmcnt(0)
	s_barrier
	s_setprio 1
	s_waitcnt lgkmcnt(0)
	v_mfma_f32_16x16x32_bf16 v[126:129], v[158:161], v[190:193], v[126:129]
	v_mfma_f32_16x16x32_bf16 v[122:125], v[166:169], v[190:193], v[122:125]
	v_mfma_f32_16x16x32_bf16 v[118:121], v[158:161], v[198:201], v[118:121]
	v_mfma_f32_16x16x32_bf16 v[110:113], v[166:169], v[198:201], v[110:113]
	v_mfma_f32_16x16x32_bf16 v[102:105], v[158:161], v[206:209], v[102:105]
	v_mfma_f32_16x16x32_bf16 v[94:97], v[166:169], v[206:209], v[94:97]
	v_mfma_f32_16x16x32_bf16 v[86:89], v[158:161], v[214:217], v[86:89]
	v_mfma_f32_16x16x32_bf16 v[78:81], v[166:169], v[214:217], v[78:81]
	v_mfma_f32_16x16x32_bf16 v[126:129], v[162:165], v[194:197], v[126:129]
	v_mfma_f32_16x16x32_bf16 v[122:125], v[170:173], v[194:197], v[122:125]
	v_mfma_f32_16x16x32_bf16 v[118:121], v[162:165], v[202:205], v[118:121]
	v_mfma_f32_16x16x32_bf16 v[110:113], v[170:173], v[202:205], v[110:113]
	v_mfma_f32_16x16x32_bf16 v[102:105], v[162:165], v[210:213], v[102:105]
	v_mfma_f32_16x16x32_bf16 v[94:97], v[170:173], v[210:213], v[94:97]
	v_mfma_f32_16x16x32_bf16 v[86:89], v[162:165], v[218:221], v[86:89]
	v_mfma_f32_16x16x32_bf16 v[78:81], v[170:173], v[218:221], v[78:81]
	s_setprio 0
	s_setprio 1
	v_mfma_f32_16x16x32_bf16 v[114:117], v[174:177], v[190:193], v[114:117]
	v_mfma_f32_16x16x32_bf16 v[106:109], v[182:185], v[190:193], v[106:109]
	v_mfma_f32_16x16x32_bf16 v[98:101], v[174:177], v[198:201], v[98:101]
	v_mfma_f32_16x16x32_bf16 v[90:93], v[182:185], v[198:201], v[90:93]
	v_mfma_f32_16x16x32_bf16 v[82:85], v[174:177], v[206:209], v[82:85]
	v_mfma_f32_16x16x32_bf16 v[74:77], v[182:185], v[206:209], v[74:77]
	v_mfma_f32_16x16x32_bf16 v[70:73], v[174:177], v[214:217], v[70:73]
	v_mfma_f32_16x16x32_bf16 v[66:69], v[182:185], v[214:217], v[66:69]
	v_mfma_f32_16x16x32_bf16 v[114:117], v[178:181], v[194:197], v[114:117]
	v_mfma_f32_16x16x32_bf16 v[106:109], v[186:189], v[194:197], v[106:109]
	v_mfma_f32_16x16x32_bf16 v[98:101], v[178:181], v[202:205], v[98:101]
	v_mfma_f32_16x16x32_bf16 v[90:93], v[186:189], v[202:205], v[90:93]
	v_mfma_f32_16x16x32_bf16 v[82:85], v[178:181], v[210:213], v[82:85]
	v_mfma_f32_16x16x32_bf16 v[74:77], v[186:189], v[210:213], v[74:77]
	v_mfma_f32_16x16x32_bf16 v[70:73], v[178:181], v[218:221], v[70:73]
	v_mfma_f32_16x16x32_bf16 v[66:69], v[186:189], v[218:221], v[66:69]
	s_setprio 0
	s_barrier
	s_add_i32 s42, s68, s46
	v_lshl_add_u64 v[222:223], v[222:223], 0, s[12:13]
	s_mov_b32 m0, s42
	ds_read_b128 v[190:193], v156 offset:49152
	ds_read_b128 v[194:197], v156 offset:50176
	ds_read_b128 v[198:201], v156 offset:51200
	ds_read_b128 v[202:205], v156 offset:52224
	ds_read_b128 v[206:209], v156 offset:53248
	ds_read_b128 v[210:213], v156 offset:54272
	ds_read_b128 v[214:217], v156 offset:55296
	ds_read_b128 v[218:221], v156 offset:56320
	global_load_lds_dwordx4 v[222:223], off
	s_add_i32 m0, s42, 0x2000
	s_add_u32 s40, s40, 0x80080
	v_lshl_add_u64 v[222:223], v[224:225], 0, s[12:13]
	s_addc_u32 s41, s41, 0
	s_add_i32 s42, s69, s46
	global_load_lds_dwordx4 v[222:223], off
	v_lshl_add_u64 v[222:223], s[40:41], 0, v[134:135]
	s_mov_b32 m0, s42
	s_nop 0
	global_load_lds_dwordx4 v[222:223], off
	v_lshl_add_u64 v[222:223], s[40:41], 0, v[130:131]
	s_add_i32 m0, s42, 0x2000
	s_nop 0
	global_load_lds_dwordx4 v[222:223], off
	v_lshl_add_u64 v[222:223], v[226:227], 0, s[12:13]
	s_mov_b32 m0, s54
	s_nop 0
	global_load_lds_dwordx4 v[222:223], off
	v_lshl_add_u64 v[222:223], v[228:229], 0, s[12:13]
	s_mov_b32 m0, s55
	s_nop 0
	global_load_lds_dwordx4 v[222:223], off
	s_waitcnt vmcnt(8)
	s_waitcnt lgkmcnt(0)
	s_barrier
	s_setprio 1
	s_waitcnt lgkmcnt(0)
	v_mfma_f32_16x16x32_bf16 v[62:65], v[158:161], v[190:193], v[62:65]
	v_mfma_f32_16x16x32_bf16 v[58:61], v[166:169], v[190:193], v[58:61]
	v_mfma_f32_16x16x32_bf16 v[54:57], v[158:161], v[198:201], v[54:57]
	v_mfma_f32_16x16x32_bf16 v[46:49], v[166:169], v[198:201], v[46:49]
	v_mfma_f32_16x16x32_bf16 v[38:41], v[158:161], v[206:209], v[38:41]
	v_mfma_f32_16x16x32_bf16 v[30:33], v[166:169], v[206:209], v[30:33]
	v_mfma_f32_16x16x32_bf16 v[22:25], v[158:161], v[214:217], v[22:25]
	v_mfma_f32_16x16x32_bf16 v[14:17], v[166:169], v[214:217], v[14:17]
	v_mfma_f32_16x16x32_bf16 v[62:65], v[162:165], v[194:197], v[62:65]
	v_mfma_f32_16x16x32_bf16 v[58:61], v[170:173], v[194:197], v[58:61]
	v_mfma_f32_16x16x32_bf16 v[54:57], v[162:165], v[202:205], v[54:57]
	v_mfma_f32_16x16x32_bf16 v[46:49], v[170:173], v[202:205], v[46:49]
	v_mfma_f32_16x16x32_bf16 v[38:41], v[162:165], v[210:213], v[38:41]
	v_mfma_f32_16x16x32_bf16 v[30:33], v[170:173], v[210:213], v[30:33]
	v_mfma_f32_16x16x32_bf16 v[22:25], v[162:165], v[218:221], v[22:25]
	v_mfma_f32_16x16x32_bf16 v[14:17], v[170:173], v[218:221], v[14:17]
	s_setprio 0
	s_setprio 1
	v_mfma_f32_16x16x32_bf16 v[50:53], v[174:177], v[190:193], v[50:53]
	v_mfma_f32_16x16x32_bf16 v[42:45], v[182:185], v[190:193], v[42:45]
	v_mfma_f32_16x16x32_bf16 v[34:37], v[174:177], v[198:201], v[34:37]
	v_mfma_f32_16x16x32_bf16 v[26:29], v[182:185], v[198:201], v[26:29]
	v_mfma_f32_16x16x32_bf16 v[18:21], v[174:177], v[206:209], v[18:21]
	v_mfma_f32_16x16x32_bf16 v[10:13], v[182:185], v[206:209], v[10:13]
	v_mfma_f32_16x16x32_bf16 v[6:9], v[174:177], v[214:217], v[6:9]
	v_mfma_f32_16x16x32_bf16 v[2:5], v[182:185], v[214:217], v[2:5]
	v_mfma_f32_16x16x32_bf16 v[50:53], v[178:181], v[194:197], v[50:53]
	v_mfma_f32_16x16x32_bf16 v[42:45], v[186:189], v[194:197], v[42:45]
	v_mfma_f32_16x16x32_bf16 v[34:37], v[178:181], v[202:205], v[34:37]
	v_mfma_f32_16x16x32_bf16 v[26:29], v[186:189], v[202:205], v[26:29]
	v_mfma_f32_16x16x32_bf16 v[18:21], v[178:181], v[210:213], v[18:21]
	v_mfma_f32_16x16x32_bf16 v[10:13], v[186:189], v[210:213], v[10:13]
	v_mfma_f32_16x16x32_bf16 v[6:9], v[178:181], v[218:221], v[6:9]
	v_mfma_f32_16x16x32_bf16 v[2:5], v[186:189], v[218:221], v[2:5]
	s_setprio 0
	s_barrier
	s_add_i32 s67, s67, 2
	s_add_u32 s38, s38, 0x100
	s_addc_u32 s39, s39, 0
	s_cmp_gt_u32 s67, 29
	s_cbranch_scc0 .LBB0_346
	s_branch .Lgk_skip_0
.Lgk_rare_0:
	s_waitcnt vmcnt(24)
	s_branch .Lgk_back_0

.Lgk_skip_0:
	s_and_b64 vcc, exec, s[14:15]
	s_cbranch_vccnz .LBB0_351
	s_mov_b64 s[30:31], -1
	s_and_b64 vcc, exec, s[34:35]
	s_cbranch_vccnz .LBB0_352

.LBB0_891:
	ds_read_b128 v[158:161], v155
	ds_read_b128 v[162:165], v155 offset:1024
	ds_read_b128 v[166:169], v155 offset:2048
	ds_read_b128 v[170:173], v155 offset:3072
	ds_read_b128 v[174:177], v156
	ds_read_b128 v[178:181], v156 offset:1024
	ds_read_b128 v[182:185], v156 offset:2048
	ds_read_b128 v[186:189], v156 offset:3072
	s_add_u32 s30, s24, s28
	s_addc_u32 s31, s25, s29
	s_add_u32 s34, s30, 0x100
	s_addc_u32 s35, s31, 0
	s_add_u32 s59, s56, s28
	s_addc_u32 s60, s57, s29
	s_cmp_eq_u32 s28, 0
	s_cselect_b64 s[30:31], -1, 0
	s_and_b64 s[30:31], s[26:27], s[30:31]
	s_cmpk_eq_i32 s28, 0x700
	v_cndmask_b32_e64 v150, 0, 1, s[30:31]
	s_cselect_b32 s35, s17, s35
	s_cselect_b32 s34, s54, s34
	v_readfirstlane_b32 s61, v150
	s_cselect_b32 s31, s15, s60
	s_cselect_b32 s30, s55, s59
	v_lshl_add_u64 v[150:151], v[148:149], 0, s[28:29]
	s_add_i32 m0, s23, 0xc000
	ds_read_b128 v[190:193], v157
	ds_read_b128 v[194:197], v157 offset:1024
	ds_read_b128 v[198:201], v157 offset:2048
	ds_read_b128 v[202:205], v157 offset:3072
	ds_read_b128 v[206:209], v157 offset:4096
	ds_read_b128 v[210:213], v157 offset:5120
	ds_read_b128 v[214:217], v157 offset:6144
	ds_read_b128 v[218:221], v157 offset:7168
	global_load_lds_dwordx4 v[150:151], off
	v_lshl_add_u64 v[150:151], v[146:147], 0, s[28:29]
	s_add_i32 m0, s23, 0xe000
	s_and_b32 s59, s61, 1
	global_load_lds_dwordx4 v[150:151], off
	s_cmp_lg_u32 s59, 0
	s_cbranch_scc1 .Lgk_rare_2
	s_waitcnt vmcnt(8)
.Lgk_back_2:
	s_waitcnt lgkmcnt(0)
	s_barrier
	s_setprio 1
	s_waitcnt lgkmcnt(0)
	v_mfma_f32_16x16x32_bf16 v[126:129], v[158:161], v[190:193], v[126:129]
	v_mfma_f32_16x16x32_bf16 v[122:125], v[166:169], v[190:193], v[122:125]
	v_mfma_f32_16x16x32_bf16 v[110:113], v[158:161], v[198:201], v[110:113]
	v_mfma_f32_16x16x32_bf16 v[106:109], v[166:169], v[198:201], v[106:109]
	v_mfma_f32_16x16x32_bf16 v[94:97], v[158:161], v[206:209], v[94:97]
	v_mfma_f32_16x16x32_bf16 v[90:93], v[166:169], v[206:209], v[90:93]
	v_mfma_f32_16x16x32_bf16 v[78:81], v[158:161], v[214:217], v[78:81]
	v_mfma_f32_16x16x32_bf16 v[74:77], v[166:169], v[214:217], v[74:77]
	v_mfma_f32_16x16x32_bf16 v[126:129], v[162:165], v[194:197], v[126:129]
	v_mfma_f32_16x16x32_bf16 v[122:125], v[170:173], v[194:197], v[122:125]
	v_mfma_f32_16x16x32_bf16 v[110:113], v[162:165], v[202:205], v[110:113]
	v_mfma_f32_16x16x32_bf16 v[106:109], v[170:173], v[202:205], v[106:109]
	v_mfma_f32_16x16x32_bf16 v[94:97], v[162:165], v[210:213], v[94:97]
	v_mfma_f32_16x16x32_bf16 v[90:93], v[170:173], v[210:213], v[90:93]
	v_mfma_f32_16x16x32_bf16 v[78:81], v[162:165], v[218:221], v[78:81]
	v_mfma_f32_16x16x32_bf16 v[74:77], v[170:173], v[218:221], v[74:77]
	s_setprio 0
	s_setprio 1
	v_mfma_f32_16x16x32_bf16 v[118:121], v[174:177], v[190:193], v[118:121]
	v_mfma_f32_16x16x32_bf16 v[114:117], v[182:185], v[190:193], v[114:117]
	v_mfma_f32_16x16x32_bf16 v[102:105], v[174:177], v[198:201], v[102:105]
	v_mfma_f32_16x16x32_bf16 v[98:101], v[182:185], v[198:201], v[98:101]
	v_mfma_f32_16x16x32_bf16 v[86:89], v[174:177], v[206:209], v[86:89]
	v_mfma_f32_16x16x32_bf16 v[82:85], v[182:185], v[206:209], v[82:85]
	v_mfma_f32_16x16x32_bf16 v[70:73], v[174:177], v[214:217], v[70:73]
	v_mfma_f32_16x16x32_bf16 v[66:69], v[182:185], v[214:217], v[66:69]
	v_mfma_f32_16x16x32_bf16 v[118:121], v[178:181], v[194:197], v[118:121]
	v_mfma_f32_16x16x32_bf16 v[114:117], v[186:189], v[194:197], v[114:117]
	v_mfma_f32_16x16x32_bf16 v[102:105], v[178:181], v[202:205], v[102:105]
	v_mfma_f32_16x16x32_bf16 v[98:101], v[186:189], v[202:205], v[98:101]
	v_mfma_f32_16x16x32_bf16 v[86:89], v[178:181], v[210:213], v[86:89]
	v_mfma_f32_16x16x32_bf16 v[82:85], v[186:189], v[210:213], v[82:85]
	v_mfma_f32_16x16x32_bf16 v[70:73], v[178:181], v[218:221], v[70:73]
	v_mfma_f32_16x16x32_bf16 v[66:69], v[186:189], v[218:221], v[66:69]
	s_setprio 0
	s_barrier
	s_add_i32 s60, s50, s41
	v_lshl_add_u64 v[150:151], s[30:31], 0, v[132:133]
	s_mov_b32 m0, s60
	ds_read_b128 v[190:193], v157 offset:16384
	ds_read_b128 v[194:197], v157 offset:17408
	ds_read_b128 v[198:201], v157 offset:18432
	ds_read_b128 v[202:205], v157 offset:19456
	ds_read_b128 v[206:209], v157 offset:20480
	ds_read_b128 v[210:213], v157 offset:21504
	ds_read_b128 v[214:217], v157 offset:22528
	ds_read_b128 v[218:221], v157 offset:23552
	global_load_lds_dwordx4 v[150:151], off
	s_add_i32 m0, s60, 0x2000
	s_add_u32 s60, s30, 0x40000
	v_lshl_add_u64 v[222:223], s[30:31], 0, v[136:137]
	s_addc_u32 s61, s31, 0
	s_add_i32 s62, s51, s41
	global_load_lds_dwordx4 v[222:223], off
	v_lshl_add_u64 v[224:225], s[60:61], 0, v[132:133]
	s_mov_b32 m0, s62
	v_lshl_add_u64 v[226:227], s[34:35], 0, v[134:135]
	global_load_lds_dwordx4 v[224:225], off
	v_lshl_add_u64 v[224:225], s[60:61], 0, v[136:137]
	s_add_i32 m0, s62, 0x2000
	s_nop 0
	global_load_lds_dwordx4 v[224:225], off
	v_lshl_add_u64 v[224:225], s[34:35], 0, v[130:131]
	s_mov_b32 m0, s23
	s_nop 0
	global_load_lds_dwordx4 v[224:225], off
	s_mov_b32 m0, s42
	s_nop 0
	global_load_lds_dwordx4 v[226:227], off
	s_cmp_lg_u32 s59, 0
	s_cbranch_scc1 .Lgk_rare_3
	s_waitcnt vmcnt(8)
.Lgk_back_3:
	s_waitcnt lgkmcnt(0)
	s_barrier
	s_setprio 1
	s_waitcnt lgkmcnt(0)
	v_mfma_f32_16x16x32_bf16 v[62:65], v[158:161], v[190:193], v[62:65]
	v_mfma_f32_16x16x32_bf16 v[58:61], v[166:169], v[190:193], v[58:61]
	v_mfma_f32_16x16x32_bf16 v[46:49], v[158:161], v[198:201], v[46:49]
	v_mfma_f32_16x16x32_bf16 v[42:45], v[166:169], v[198:201], v[42:45]
	v_mfma_f32_16x16x32_bf16 v[30:33], v[158:161], v[206:209], v[30:33]
	v_mfma_f32_16x16x32_bf16 v[26:29], v[166:169], v[206:209], v[26:29]
	v_mfma_f32_16x16x32_bf16 v[14:17], v[158:161], v[214:217], v[14:17]
	v_mfma_f32_16x16x32_bf16 v[10:13], v[166:169], v[214:217], v[10:13]
	v_mfma_f32_16x16x32_bf16 v[62:65], v[162:165], v[194:197], v[62:65]
	v_mfma_f32_16x16x32_bf16 v[58:61], v[170:173], v[194:197], v[58:61]
	v_mfma_f32_16x16x32_bf16 v[46:49], v[162:165], v[202:205], v[46:49]
	v_mfma_f32_16x16x32_bf16 v[42:45], v[170:173], v[202:205], v[42:45]
	v_mfma_f32_16x16x32_bf16 v[30:33], v[162:165], v[210:213], v[30:33]
	v_mfma_f32_16x16x32_bf16 v[26:29], v[170:173], v[210:213], v[26:29]
	v_mfma_f32_16x16x32_bf16 v[14:17], v[162:165], v[218:221], v[14:17]
	v_mfma_f32_16x16x32_bf16 v[10:13], v[170:173], v[218:221], v[10:13]
	s_setprio 0
	s_setprio 1
	v_mfma_f32_16x16x32_bf16 v[54:57], v[174:177], v[190:193], v[54:57]
	v_mfma_f32_16x16x32_bf16 v[50:53], v[182:185], v[190:193], v[50:53]
	v_mfma_f32_16x16x32_bf16 v[38:41], v[174:177], v[198:201], v[38:41]
	v_mfma_f32_16x16x32_bf16 v[34:37], v[182:185], v[198:201], v[34:37]
	v_mfma_f32_16x16x32_bf16 v[22:25], v[174:177], v[206:209], v[22:25]
	v_mfma_f32_16x16x32_bf16 v[18:21], v[182:185], v[206:209], v[18:21]
	v_mfma_f32_16x16x32_bf16 v[6:9], v[174:177], v[214:217], v[6:9]
	v_mfma_f32_16x16x32_bf16 v[2:5], v[182:185], v[214:217], v[2:5]
	v_mfma_f32_16x16x32_bf16 v[54:57], v[178:181], v[194:197], v[54:57]
	v_mfma_f32_16x16x32_bf16 v[50:53], v[186:189], v[194:197], v[50:53]
	v_mfma_f32_16x16x32_bf16 v[38:41], v[178:181], v[202:205], v[38:41]
	v_mfma_f32_16x16x32_bf16 v[34:37], v[186:189], v[202:205], v[34:37]
	v_mfma_f32_16x16x32_bf16 v[22:25], v[178:181], v[210:213], v[22:25]
	v_mfma_f32_16x16x32_bf16 v[18:21], v[186:189], v[210:213], v[18:21]
	v_mfma_f32_16x16x32_bf16 v[6:9], v[178:181], v[218:221], v[6:9]
	v_mfma_f32_16x16x32_bf16 v[2:5], v[186:189], v[218:221], v[2:5]
	s_setprio 0
	s_barrier
	s_add_i32 s59, 0, 0x18000
	s_add_i32 s60, 0, 0x1c000
	v_add_u32_e32 v170, s59, v152
	v_add_u32_e32 v186, s60, v152
	ds_read_b128 v[158:161], v170
	ds_read_b128 v[162:165], v170 offset:1024
	ds_read_b128 v[166:169], v170 offset:2048
	ds_read_b128 v[170:173], v170 offset:3072
	ds_read_b128 v[174:177], v186
	ds_read_b128 v[178:181], v186 offset:1024
	ds_read_b128 v[182:185], v186 offset:2048
	ds_read_b128 v[186:189], v186 offset:3072
	s_add_u32 s34, s34, 0x40000
	s_addc_u32 s35, s35, 0
	s_mov_b32 m0, s43
	v_lshl_add_u64 v[228:229], s[34:35], 0, v[130:131]
	ds_read_b128 v[190:193], v157 offset:32768
	ds_read_b128 v[194:197], v157 offset:33792
	ds_read_b128 v[198:201], v157 offset:34816
	ds_read_b128 v[202:205], v157 offset:35840
	ds_read_b128 v[206:209], v157 offset:36864
	ds_read_b128 v[210:213], v157 offset:37888
	ds_read_b128 v[214:217], v157 offset:38912
	ds_read_b128 v[218:221], v157 offset:39936
	global_load_lds_dwordx4 v[228:229], off
	v_lshl_add_u64 v[228:229], s[34:35], 0, v[134:135]
	s_mov_b32 m0, s44
	s_nop 0
	global_load_lds_dwordx4 v[228:229], off
	s_waitcnt vmcnt(8)
	s_waitcnt lgkmcnt(0)
	s_barrier
	s_setprio 1
	s_waitcnt lgkmcnt(0)
	v_mfma_f32_16x16x32_bf16 v[126:129], v[158:161], v[190:193], v[126:129]
	v_mfma_f32_16x16x32_bf16 v[122:125], v[166:169], v[190:193], v[122:125]
	v_mfma_f32_16x16x32_bf16 v[110:113], v[158:161], v[198:201], v[110:113]
	v_mfma_f32_16x16x32_bf16 v[106:109], v[166:169], v[198:201], v[106:109]
	v_mfma_f32_16x16x32_bf16 v[94:97], v[158:161], v[206:209], v[94:97]
	v_mfma_f32_16x16x32_bf16 v[90:93], v[166:169], v[206:209], v[90:93]
	v_mfma_f32_16x16x32_bf16 v[78:81], v[158:161], v[214:217], v[78:81]
	v_mfma_f32_16x16x32_bf16 v[74:77], v[166:169], v[214:217], v[74:77]
	v_mfma_f32_16x16x32_bf16 v[126:129], v[162:165], v[194:197], v[126:129]
	v_mfma_f32_16x16x32_bf16 v[122:125], v[170:173], v[194:197], v[122:125]
	v_mfma_f32_16x16x32_bf16 v[110:113], v[162:165], v[202:205], v[110:113]
	v_mfma_f32_16x16x32_bf16 v[106:109], v[170:173], v[202:205], v[106:109]
	v_mfma_f32_16x16x32_bf16 v[94:97], v[162:165], v[210:213], v[94:97]
	v_mfma_f32_16x16x32_bf16 v[90:93], v[170:173], v[210:213], v[90:93]
	v_mfma_f32_16x16x32_bf16 v[78:81], v[162:165], v[218:221], v[78:81]
	v_mfma_f32_16x16x32_bf16 v[74:77], v[170:173], v[218:221], v[74:77]
	s_setprio 0
	s_setprio 1
	v_mfma_f32_16x16x32_bf16 v[118:121], v[174:177], v[190:193], v[118:121]
	v_mfma_f32_16x16x32_bf16 v[114:117], v[182:185], v[190:193], v[114:117]
	v_mfma_f32_16x16x32_bf16 v[102:105], v[174:177], v[198:201], v[102:105]
	v_mfma_f32_16x16x32_bf16 v[98:101], v[182:185], v[198:201], v[98:101]
	v_mfma_f32_16x16x32_bf16 v[86:89], v[174:177], v[206:209], v[86:89]
	v_mfma_f32_16x16x32_bf16 v[82:85], v[182:185], v[206:209], v[82:85]
	v_mfma_f32_16x16x32_bf16 v[70:73], v[174:177], v[214:217], v[70:73]
	v_mfma_f32_16x16x32_bf16 v[66:69], v[182:185], v[214:217], v[66:69]
	v_mfma_f32_16x16x32_bf16 v[118:121], v[178:181], v[194:197], v[118:121]
	v_mfma_f32_16x16x32_bf16 v[114:117], v[186:189], v[194:197], v[114:117]
	v_mfma_f32_16x16x32_bf16 v[102:105], v[178:181], v[202:205], v[102:105]
	v_mfma_f32_16x16x32_bf16 v[98:101], v[186:189], v[202:205], v[98:101]
	v_mfma_f32_16x16x32_bf16 v[86:89], v[178:181], v[210:213], v[86:89]
	v_mfma_f32_16x16x32_bf16 v[82:85], v[186:189], v[210:213], v[82:85]
	v_mfma_f32_16x16x32_bf16 v[70:73], v[178:181], v[218:221], v[70:73]
	v_mfma_f32_16x16x32_bf16 v[66:69], v[186:189], v[218:221], v[66:69]
	s_setprio 0
	s_barrier
	s_add_i32 s34, s59, s41
	v_lshl_add_u64 v[150:151], v[150:151], 0, s[10:11]
	s_mov_b32 m0, s34
	ds_read_b128 v[190:193], v157 offset:49152
	ds_read_b128 v[194:197], v157 offset:50176
	ds_read_b128 v[198:201], v157 offset:51200
	ds_read_b128 v[202:205], v157 offset:52224
	ds_read_b128 v[206:209], v157 offset:53248
	ds_read_b128 v[210:213], v157 offset:54272
	ds_read_b128 v[214:217], v157 offset:55296
	ds_read_b128 v[218:221], v157 offset:56320
	global_load_lds_dwordx4 v[150:151], off
	s_add_i32 m0, s34, 0x2000
	s_add_u32 s30, s30, 0x40080
	v_lshl_add_u64 v[150:151], v[222:223], 0, s[10:11]
	s_addc_u32 s31, s31, 0
	s_add_i32 s34, s60, s41
	global_load_lds_dwordx4 v[150:151], off
	v_lshl_add_u64 v[150:151], s[30:31], 0, v[132:133]
	s_mov_b32 m0, s34
	s_nop 0
	global_load_lds_dwordx4 v[150:151], off
	v_lshl_add_u64 v[150:151], s[30:31], 0, v[136:137]
	s_add_i32 m0, s34, 0x2000
	s_nop 0
	global_load_lds_dwordx4 v[150:151], off
	v_lshl_add_u64 v[150:151], v[224:225], 0, s[10:11]
	s_mov_b32 m0, s46
	s_nop 0
	global_load_lds_dwordx4 v[150:151], off
	v_lshl_add_u64 v[150:151], v[226:227], 0, s[10:11]
	s_mov_b32 m0, s47
	s_nop 0
	global_load_lds_dwordx4 v[150:151], off
	s_waitcnt vmcnt(8)
	s_waitcnt lgkmcnt(0)
	s_barrier
	s_setprio 1
	s_waitcnt lgkmcnt(0)
	v_mfma_f32_16x16x32_bf16 v[62:65], v[158:161], v[190:193], v[62:65]
	v_mfma_f32_16x16x32_bf16 v[58:61], v[166:169], v[190:193], v[58:61]
	v_mfma_f32_16x16x32_bf16 v[46:49], v[158:161], v[198:201], v[46:49]
	v_mfma_f32_16x16x32_bf16 v[42:45], v[166:169], v[198:201], v[42:45]
	v_mfma_f32_16x16x32_bf16 v[30:33], v[158:161], v[206:209], v[30:33]
	v_mfma_f32_16x16x32_bf16 v[26:29], v[166:169], v[206:209], v[26:29]
	v_mfma_f32_16x16x32_bf16 v[14:17], v[158:161], v[214:217], v[14:17]
	v_mfma_f32_16x16x32_bf16 v[10:13], v[166:169], v[214:217], v[10:13]
	v_mfma_f32_16x16x32_bf16 v[62:65], v[162:165], v[194:197], v[62:65]
	v_mfma_f32_16x16x32_bf16 v[58:61], v[170:173], v[194:197], v[58:61]
	v_mfma_f32_16x16x32_bf16 v[46:49], v[162:165], v[202:205], v[46:49]
	v_mfma_f32_16x16x32_bf16 v[42:45], v[170:173], v[202:205], v[42:45]
	v_mfma_f32_16x16x32_bf16 v[30:33], v[162:165], v[210:213], v[30:33]
	v_mfma_f32_16x16x32_bf16 v[26:29], v[170:173], v[210:213], v[26:29]
	v_mfma_f32_16x16x32_bf16 v[14:17], v[162:165], v[218:221], v[14:17]
	v_mfma_f32_16x16x32_bf16 v[10:13], v[170:173], v[218:221], v[10:13]
	s_setprio 0
	s_setprio 1
	v_mfma_f32_16x16x32_bf16 v[54:57], v[174:177], v[190:193], v[54:57]
	v_mfma_f32_16x16x32_bf16 v[50:53], v[182:185], v[190:193], v[50:53]
	v_mfma_f32_16x16x32_bf16 v[38:41], v[174:177], v[198:201], v[38:41]
	v_mfma_f32_16x16x32_bf16 v[34:37], v[182:185], v[198:201], v[34:37]
	v_mfma_f32_16x16x32_bf16 v[22:25], v[174:177], v[206:209], v[22:25]
	v_mfma_f32_16x16x32_bf16 v[18:21], v[182:185], v[206:209], v[18:21]
	v_mfma_f32_16x16x32_bf16 v[6:9], v[174:177], v[214:217], v[6:9]
	v_mfma_f32_16x16x32_bf16 v[2:5], v[182:185], v[214:217], v[2:5]
	v_mfma_f32_16x16x32_bf16 v[54:57], v[178:181], v[194:197], v[54:57]
	v_mfma_f32_16x16x32_bf16 v[50:53], v[186:189], v[194:197], v[50:53]
	v_mfma_f32_16x16x32_bf16 v[38:41], v[178:181], v[202:205], v[38:41]
	v_mfma_f32_16x16x32_bf16 v[34:37], v[186:189], v[202:205], v[34:37]
	v_mfma_f32_16x16x32_bf16 v[22:25], v[178:181], v[210:213], v[22:25]
	v_mfma_f32_16x16x32_bf16 v[18:21], v[186:189], v[210:213], v[18:21]
	v_mfma_f32_16x16x32_bf16 v[6:9], v[178:181], v[218:221], v[6:9]
	v_mfma_f32_16x16x32_bf16 v[2:5], v[186:189], v[218:221], v[2:5]
	s_setprio 0
	s_barrier
	s_add_i32 s58, s58, 2
	s_add_u32 s28, s28, 0x100
	s_addc_u32 s29, s29, 0
	s_cmp_gt_u32 s58, 13
	s_cbranch_scc0 .LBB0_891
	s_branch .Lgk_skip_1

.Lgk_skip_1:
	s_and_b64 vcc, exec, s[12:13]
	s_cbranch_vccz .LBB0_894
	s_barrier

.LBB0_915:
	ds_read_b128 v[150:153], v157
	ds_read_b128 v[160:163], v157 offset:1024
	ds_read_b128 v[164:167], v157 offset:2048
	ds_read_b128 v[168:171], v157 offset:3072
	ds_read_b128 v[172:175], v158
	ds_read_b128 v[176:179], v158 offset:1024
	ds_read_b128 v[180:183], v158 offset:2048
	ds_read_b128 v[184:187], v158 offset:3072
	s_add_u32 s30, s24, s28
	s_addc_u32 s31, s25, s29
	s_add_u32 s34, s30, 0x100
	s_addc_u32 s35, s31, 0
	s_add_u32 s59, s56, s28
	s_addc_u32 s60, s57, s29
	s_cmp_eq_u32 s28, 0
	s_cselect_b64 s[30:31], -1, 0
	s_and_b64 s[30:31], s[26:27], s[30:31]
	s_cmpk_eq_i32 s28, 0x700
	v_cndmask_b32_e64 v188, 0, 1, s[30:31]
	s_cselect_b32 s35, s17, s35
	s_cselect_b32 s34, s54, s34
	v_readfirstlane_b32 s61, v188
	s_cselect_b32 s31, s15, s60
	s_cselect_b32 s30, s55, s59
	v_lshl_add_u64 v[220:221], v[148:149], 0, s[28:29]
	s_add_i32 m0, s23, 0xc000
	ds_read_b128 v[188:191], v159
	ds_read_b128 v[192:195], v159 offset:1024
	ds_read_b128 v[196:199], v159 offset:2048
	ds_read_b128 v[200:203], v159 offset:3072
	ds_read_b128 v[204:207], v159 offset:4096
	ds_read_b128 v[208:211], v159 offset:5120
	ds_read_b128 v[212:215], v159 offset:6144
	ds_read_b128 v[216:219], v159 offset:7168
	global_load_lds_dwordx4 v[220:221], off
	v_lshl_add_u64 v[220:221], v[146:147], 0, s[28:29]
	s_add_i32 m0, s23, 0xe000
	s_and_b32 s59, s61, 1
	global_load_lds_dwordx4 v[220:221], off
	s_cmp_lg_u32 s59, 0
	s_cbranch_scc1 .Lgk_rare_4
	s_waitcnt vmcnt(8)
.Lgk_back_4:
	s_waitcnt lgkmcnt(0)
	s_barrier
	s_setprio 1
	s_waitcnt lgkmcnt(0)
	v_mfma_f32_16x16x32_bf16 v[126:129], v[150:153], v[188:191], v[126:129]
	v_mfma_f32_16x16x32_bf16 v[122:125], v[164:167], v[188:191], v[122:125]
	v_mfma_f32_16x16x32_bf16 v[110:113], v[150:153], v[196:199], v[110:113]
	v_mfma_f32_16x16x32_bf16 v[106:109], v[164:167], v[196:199], v[106:109]
	v_mfma_f32_16x16x32_bf16 v[94:97], v[150:153], v[204:207], v[94:97]
	v_mfma_f32_16x16x32_bf16 v[90:93], v[164:167], v[204:207], v[90:93]
	v_mfma_f32_16x16x32_bf16 v[78:81], v[150:153], v[212:215], v[78:81]
	v_mfma_f32_16x16x32_bf16 v[74:77], v[164:167], v[212:215], v[74:77]
	v_mfma_f32_16x16x32_bf16 v[126:129], v[160:163], v[192:195], v[126:129]
	v_mfma_f32_16x16x32_bf16 v[122:125], v[168:171], v[192:195], v[122:125]
	v_mfma_f32_16x16x32_bf16 v[110:113], v[160:163], v[200:203], v[110:113]
	v_mfma_f32_16x16x32_bf16 v[106:109], v[168:171], v[200:203], v[106:109]
	v_mfma_f32_16x16x32_bf16 v[94:97], v[160:163], v[208:211], v[94:97]
	v_mfma_f32_16x16x32_bf16 v[90:93], v[168:171], v[208:211], v[90:93]
	v_mfma_f32_16x16x32_bf16 v[78:81], v[160:163], v[216:219], v[78:81]
	v_mfma_f32_16x16x32_bf16 v[74:77], v[168:171], v[216:219], v[74:77]
	s_setprio 0
	s_setprio 1
	v_mfma_f32_16x16x32_bf16 v[118:121], v[172:175], v[188:191], v[118:121]
	v_mfma_f32_16x16x32_bf16 v[114:117], v[180:183], v[188:191], v[114:117]
	v_mfma_f32_16x16x32_bf16 v[102:105], v[172:175], v[196:199], v[102:105]
	v_mfma_f32_16x16x32_bf16 v[98:101], v[180:183], v[196:199], v[98:101]
	v_mfma_f32_16x16x32_bf16 v[86:89], v[172:175], v[204:207], v[86:89]
	v_mfma_f32_16x16x32_bf16 v[82:85], v[180:183], v[204:207], v[82:85]
	v_mfma_f32_16x16x32_bf16 v[70:73], v[172:175], v[212:215], v[70:73]
	v_mfma_f32_16x16x32_bf16 v[66:69], v[180:183], v[212:215], v[66:69]
	v_mfma_f32_16x16x32_bf16 v[118:121], v[176:179], v[192:195], v[118:121]
	v_mfma_f32_16x16x32_bf16 v[114:117], v[184:187], v[192:195], v[114:117]
	v_mfma_f32_16x16x32_bf16 v[102:105], v[176:179], v[200:203], v[102:105]
	v_mfma_f32_16x16x32_bf16 v[98:101], v[184:187], v[200:203], v[98:101]
	v_mfma_f32_16x16x32_bf16 v[86:89], v[176:179], v[208:211], v[86:89]
	v_mfma_f32_16x16x32_bf16 v[82:85], v[184:187], v[208:211], v[82:85]
	v_mfma_f32_16x16x32_bf16 v[70:73], v[176:179], v[216:219], v[70:73]
	v_mfma_f32_16x16x32_bf16 v[66:69], v[184:187], v[216:219], v[66:69]
	s_setprio 0
	s_barrier
	s_add_i32 s60, s50, s41
	v_lshl_add_u64 v[220:221], s[30:31], 0, v[132:133]
	s_mov_b32 m0, s60
	ds_read_b128 v[188:191], v159 offset:16384
	ds_read_b128 v[192:195], v159 offset:17408
	ds_read_b128 v[196:199], v159 offset:18432
	ds_read_b128 v[200:203], v159 offset:19456
	ds_read_b128 v[204:207], v159 offset:20480
	ds_read_b128 v[208:211], v159 offset:21504
	ds_read_b128 v[212:215], v159 offset:22528
	ds_read_b128 v[216:219], v159 offset:23552
	global_load_lds_dwordx4 v[220:221], off
	s_add_i32 m0, s60, 0x2000
	s_add_u32 s60, s30, 0x40000
	v_lshl_add_u64 v[222:223], s[30:31], 0, v[136:137]
	s_addc_u32 s61, s31, 0
	s_add_i32 s62, s51, s41
	global_load_lds_dwordx4 v[222:223], off
	v_lshl_add_u64 v[224:225], s[60:61], 0, v[132:133]
	s_mov_b32 m0, s62
	v_lshl_add_u64 v[226:227], s[34:35], 0, v[134:135]
	global_load_lds_dwordx4 v[224:225], off
	v_lshl_add_u64 v[224:225], s[60:61], 0, v[136:137]
	s_add_i32 m0, s62, 0x2000
	s_nop 0
	global_load_lds_dwordx4 v[224:225], off
	v_lshl_add_u64 v[224:225], s[34:35], 0, v[130:131]
	s_mov_b32 m0, s23
	s_nop 0
	global_load_lds_dwordx4 v[224:225], off
	s_mov_b32 m0, s42
	s_nop 0
	global_load_lds_dwordx4 v[226:227], off
	s_cmp_lg_u32 s59, 0
	s_cbranch_scc1 .Lgk_rare_5
	s_waitcnt vmcnt(8)
.Lgk_back_5:
	s_waitcnt lgkmcnt(0)
	s_barrier
	s_setprio 1
	s_waitcnt lgkmcnt(0)
	v_mfma_f32_16x16x32_bf16 v[62:65], v[150:153], v[188:191], v[62:65]
	v_mfma_f32_16x16x32_bf16 v[58:61], v[164:167], v[188:191], v[58:61]
	v_mfma_f32_16x16x32_bf16 v[46:49], v[150:153], v[196:199], v[46:49]
	v_mfma_f32_16x16x32_bf16 v[42:45], v[164:167], v[196:199], v[42:45]
	v_mfma_f32_16x16x32_bf16 v[30:33], v[150:153], v[204:207], v[30:33]
	v_mfma_f32_16x16x32_bf16 v[26:29], v[164:167], v[204:207], v[26:29]
	v_mfma_f32_16x16x32_bf16 v[14:17], v[150:153], v[212:215], v[14:17]
	v_mfma_f32_16x16x32_bf16 v[10:13], v[164:167], v[212:215], v[10:13]
	v_mfma_f32_16x16x32_bf16 v[62:65], v[160:163], v[192:195], v[62:65]
	v_mfma_f32_16x16x32_bf16 v[58:61], v[168:171], v[192:195], v[58:61]
	v_mfma_f32_16x16x32_bf16 v[46:49], v[160:163], v[200:203], v[46:49]
	v_mfma_f32_16x16x32_bf16 v[42:45], v[168:171], v[200:203], v[42:45]
	v_mfma_f32_16x16x32_bf16 v[30:33], v[160:163], v[208:211], v[30:33]
	v_mfma_f32_16x16x32_bf16 v[26:29], v[168:171], v[208:211], v[26:29]
	v_mfma_f32_16x16x32_bf16 v[14:17], v[160:163], v[216:219], v[14:17]
	v_mfma_f32_16x16x32_bf16 v[10:13], v[168:171], v[216:219], v[10:13]
	s_setprio 0
	s_setprio 1
	v_mfma_f32_16x16x32_bf16 v[54:57], v[172:175], v[188:191], v[54:57]
	v_mfma_f32_16x16x32_bf16 v[50:53], v[180:183], v[188:191], v[50:53]
	v_mfma_f32_16x16x32_bf16 v[38:41], v[172:175], v[196:199], v[38:41]
	v_mfma_f32_16x16x32_bf16 v[34:37], v[180:183], v[196:199], v[34:37]
	v_mfma_f32_16x16x32_bf16 v[22:25], v[172:175], v[204:207], v[22:25]
	v_mfma_f32_16x16x32_bf16 v[18:21], v[180:183], v[204:207], v[18:21]
	v_mfma_f32_16x16x32_bf16 v[6:9], v[172:175], v[212:215], v[6:9]
	v_mfma_f32_16x16x32_bf16 v[2:5], v[180:183], v[212:215], v[2:5]
	v_mfma_f32_16x16x32_bf16 v[54:57], v[176:179], v[192:195], v[54:57]
	v_mfma_f32_16x16x32_bf16 v[50:53], v[184:187], v[192:195], v[50:53]
	v_mfma_f32_16x16x32_bf16 v[38:41], v[176:179], v[200:203], v[38:41]
	v_mfma_f32_16x16x32_bf16 v[34:37], v[184:187], v[200:203], v[34:37]
	v_mfma_f32_16x16x32_bf16 v[22:25], v[176:179], v[208:211], v[22:25]
	v_mfma_f32_16x16x32_bf16 v[18:21], v[184:187], v[208:211], v[18:21]
	v_mfma_f32_16x16x32_bf16 v[6:9], v[176:179], v[216:219], v[6:9]
	v_mfma_f32_16x16x32_bf16 v[2:5], v[184:187], v[216:219], v[2:5]
	s_setprio 0
	s_barrier
	s_add_i32 s59, 0, 0x18000
	s_add_i32 s60, 0, 0x1c000
	v_add_u32_e32 v168, s59, v155
	v_add_u32_e32 v184, s60, v155
	ds_read_b128 v[150:153], v168
	ds_read_b128 v[160:163], v168 offset:1024
	ds_read_b128 v[164:167], v168 offset:2048
	ds_read_b128 v[168:171], v168 offset:3072
	ds_read_b128 v[172:175], v184
	ds_read_b128 v[176:179], v184 offset:1024
	ds_read_b128 v[180:183], v184 offset:2048
	ds_read_b128 v[184:187], v184 offset:3072
	s_add_u32 s34, s34, 0x40000
	s_addc_u32 s35, s35, 0
	s_mov_b32 m0, s43
	v_lshl_add_u64 v[228:229], s[34:35], 0, v[130:131]
	ds_read_b128 v[188:191], v159 offset:32768
	ds_read_b128 v[192:195], v159 offset:33792
	ds_read_b128 v[196:199], v159 offset:34816
	ds_read_b128 v[200:203], v159 offset:35840
	ds_read_b128 v[204:207], v159 offset:36864
	ds_read_b128 v[208:211], v159 offset:37888
	ds_read_b128 v[212:215], v159 offset:38912
	ds_read_b128 v[216:219], v159 offset:39936
	global_load_lds_dwordx4 v[228:229], off
	v_lshl_add_u64 v[228:229], s[34:35], 0, v[134:135]
	s_mov_b32 m0, s44
	s_nop 0
	global_load_lds_dwordx4 v[228:229], off
	s_waitcnt vmcnt(8)
	s_waitcnt lgkmcnt(0)
	s_barrier
	s_setprio 1
	s_waitcnt lgkmcnt(0)
	v_mfma_f32_16x16x32_bf16 v[126:129], v[150:153], v[188:191], v[126:129]
	v_mfma_f32_16x16x32_bf16 v[122:125], v[164:167], v[188:191], v[122:125]
	v_mfma_f32_16x16x32_bf16 v[110:113], v[150:153], v[196:199], v[110:113]
	v_mfma_f32_16x16x32_bf16 v[106:109], v[164:167], v[196:199], v[106:109]
	v_mfma_f32_16x16x32_bf16 v[94:97], v[150:153], v[204:207], v[94:97]
	v_mfma_f32_16x16x32_bf16 v[90:93], v[164:167], v[204:207], v[90:93]
	v_mfma_f32_16x16x32_bf16 v[78:81], v[150:153], v[212:215], v[78:81]
	v_mfma_f32_16x16x32_bf16 v[74:77], v[164:167], v[212:215], v[74:77]
	v_mfma_f32_16x16x32_bf16 v[126:129], v[160:163], v[192:195], v[126:129]
	v_mfma_f32_16x16x32_bf16 v[122:125], v[168:171], v[192:195], v[122:125]
	v_mfma_f32_16x16x32_bf16 v[110:113], v[160:163], v[200:203], v[110:113]
	v_mfma_f32_16x16x32_bf16 v[106:109], v[168:171], v[200:203], v[106:109]
	v_mfma_f32_16x16x32_bf16 v[94:97], v[160:163], v[208:211], v[94:97]
	v_mfma_f32_16x16x32_bf16 v[90:93], v[168:171], v[208:211], v[90:93]
	v_mfma_f32_16x16x32_bf16 v[78:81], v[160:163], v[216:219], v[78:81]
	v_mfma_f32_16x16x32_bf16 v[74:77], v[168:171], v[216:219], v[74:77]
	s_setprio 0
	s_setprio 1
	v_mfma_f32_16x16x32_bf16 v[118:121], v[172:175], v[188:191], v[118:121]
	v_mfma_f32_16x16x32_bf16 v[114:117], v[180:183], v[188:191], v[114:117]
	v_mfma_f32_16x16x32_bf16 v[102:105], v[172:175], v[196:199], v[102:105]
	v_mfma_f32_16x16x32_bf16 v[98:101], v[180:183], v[196:199], v[98:101]
	v_mfma_f32_16x16x32_bf16 v[86:89], v[172:175], v[204:207], v[86:89]
	v_mfma_f32_16x16x32_bf16 v[82:85], v[180:183], v[204:207], v[82:85]
	v_mfma_f32_16x16x32_bf16 v[70:73], v[172:175], v[212:215], v[70:73]
	v_mfma_f32_16x16x32_bf16 v[66:69], v[180:183], v[212:215], v[66:69]
	v_mfma_f32_16x16x32_bf16 v[118:121], v[176:179], v[192:195], v[118:121]
	v_mfma_f32_16x16x32_bf16 v[114:117], v[184:187], v[192:195], v[114:117]
	v_mfma_f32_16x16x32_bf16 v[102:105], v[176:179], v[200:203], v[102:105]
	v_mfma_f32_16x16x32_bf16 v[98:101], v[184:187], v[200:203], v[98:101]
	v_mfma_f32_16x16x32_bf16 v[86:89], v[176:179], v[208:211], v[86:89]
	v_mfma_f32_16x16x32_bf16 v[82:85], v[184:187], v[208:211], v[82:85]
	v_mfma_f32_16x16x32_bf16 v[70:73], v[176:179], v[216:219], v[70:73]
	v_mfma_f32_16x16x32_bf16 v[66:69], v[184:187], v[216:219], v[66:69]
	s_setprio 0
	s_barrier
	s_add_i32 s34, s59, s41
	v_lshl_add_u64 v[220:221], v[220:221], 0, s[10:11]
	s_mov_b32 m0, s34
	ds_read_b128 v[188:191], v159 offset:49152
	ds_read_b128 v[192:195], v159 offset:50176
	ds_read_b128 v[196:199], v159 offset:51200
	ds_read_b128 v[200:203], v159 offset:52224
	ds_read_b128 v[204:207], v159 offset:53248
	ds_read_b128 v[208:211], v159 offset:54272
	ds_read_b128 v[212:215], v159 offset:55296
	ds_read_b128 v[216:219], v159 offset:56320
	global_load_lds_dwordx4 v[220:221], off
	s_add_i32 m0, s34, 0x2000
	s_add_u32 s30, s30, 0x40080
	v_lshl_add_u64 v[220:221], v[222:223], 0, s[10:11]
	s_addc_u32 s31, s31, 0
	s_add_i32 s34, s60, s41
	global_load_lds_dwordx4 v[220:221], off
	v_lshl_add_u64 v[220:221], s[30:31], 0, v[132:133]
	s_mov_b32 m0, s34
	s_nop 0
	global_load_lds_dwordx4 v[220:221], off
	v_lshl_add_u64 v[220:221], s[30:31], 0, v[136:137]
	s_add_i32 m0, s34, 0x2000
	s_nop 0
	global_load_lds_dwordx4 v[220:221], off
	v_lshl_add_u64 v[220:221], v[224:225], 0, s[10:11]
	s_mov_b32 m0, s46
	s_nop 0
	global_load_lds_dwordx4 v[220:221], off
	v_lshl_add_u64 v[220:221], v[226:227], 0, s[10:11]
	s_mov_b32 m0, s47
	s_nop 0
	global_load_lds_dwordx4 v[220:221], off
	s_waitcnt vmcnt(8)
	s_waitcnt lgkmcnt(0)
	s_barrier
	s_setprio 1
	s_waitcnt lgkmcnt(0)
	v_mfma_f32_16x16x32_bf16 v[62:65], v[150:153], v[188:191], v[62:65]
	v_mfma_f32_16x16x32_bf16 v[58:61], v[164:167], v[188:191], v[58:61]
	v_mfma_f32_16x16x32_bf16 v[46:49], v[150:153], v[196:199], v[46:49]
	v_mfma_f32_16x16x32_bf16 v[42:45], v[164:167], v[196:199], v[42:45]
	v_mfma_f32_16x16x32_bf16 v[30:33], v[150:153], v[204:207], v[30:33]
	v_mfma_f32_16x16x32_bf16 v[26:29], v[164:167], v[204:207], v[26:29]
	v_mfma_f32_16x16x32_bf16 v[14:17], v[150:153], v[212:215], v[14:17]
	v_mfma_f32_16x16x32_bf16 v[10:13], v[164:167], v[212:215], v[10:13]
	v_mfma_f32_16x16x32_bf16 v[62:65], v[160:163], v[192:195], v[62:65]
	v_mfma_f32_16x16x32_bf16 v[58:61], v[168:171], v[192:195], v[58:61]
	v_mfma_f32_16x16x32_bf16 v[46:49], v[160:163], v[200:203], v[46:49]
	v_mfma_f32_16x16x32_bf16 v[42:45], v[168:171], v[200:203], v[42:45]
	v_mfma_f32_16x16x32_bf16 v[30:33], v[160:163], v[208:211], v[30:33]
	v_mfma_f32_16x16x32_bf16 v[26:29], v[168:171], v[208:211], v[26:29]
	v_mfma_f32_16x16x32_bf16 v[14:17], v[160:163], v[216:219], v[14:17]
	v_mfma_f32_16x16x32_bf16 v[10:13], v[168:171], v[216:219], v[10:13]
	s_setprio 0
	s_setprio 1
	v_mfma_f32_16x16x32_bf16 v[54:57], v[172:175], v[188:191], v[54:57]
	v_mfma_f32_16x16x32_bf16 v[50:53], v[180:183], v[188:191], v[50:53]
	v_mfma_f32_16x16x32_bf16 v[38:41], v[172:175], v[196:199], v[38:41]
	v_mfma_f32_16x16x32_bf16 v[34:37], v[180:183], v[196:199], v[34:37]
	v_mfma_f32_16x16x32_bf16 v[22:25], v[172:175], v[204:207], v[22:25]
	v_mfma_f32_16x16x32_bf16 v[18:21], v[180:183], v[204:207], v[18:21]
	v_mfma_f32_16x16x32_bf16 v[6:9], v[172:175], v[212:215], v[6:9]
	v_mfma_f32_16x16x32_bf16 v[2:5], v[180:183], v[212:215], v[2:5]
	v_mfma_f32_16x16x32_bf16 v[54:57], v[176:179], v[192:195], v[54:57]
	v_mfma_f32_16x16x32_bf16 v[50:53], v[184:187], v[192:195], v[50:53]
	v_mfma_f32_16x16x32_bf16 v[38:41], v[176:179], v[200:203], v[38:41]
	v_mfma_f32_16x16x32_bf16 v[34:37], v[184:187], v[200:203], v[34:37]
	v_mfma_f32_16x16x32_bf16 v[22:25], v[176:179], v[208:211], v[22:25]
	v_mfma_f32_16x16x32_bf16 v[18:21], v[184:187], v[208:211], v[18:21]
	v_mfma_f32_16x16x32_bf16 v[6:9], v[176:179], v[216:219], v[6:9]
	v_mfma_f32_16x16x32_bf16 v[2:5], v[184:187], v[216:219], v[2:5]
	s_setprio 0
	s_barrier
	s_add_i32 s58, s58, 2
	s_add_u32 s28, s28, 0x100
	s_addc_u32 s29, s29, 0
	s_cmp_gt_u32 s58, 13
	s_cbranch_scc0 .LBB0_915
	s_branch .Lgk_skip_2

.LBB0_1009:
	ds_read_b128 v[156:159], v152
	ds_read_b128 v[160:163], v152 offset:1024
	ds_read_b128 v[164:167], v152 offset:2048
	ds_read_b128 v[168:171], v152 offset:3072
	ds_read_b128 v[172:175], v153
	ds_read_b128 v[176:179], v153 offset:1024
	ds_read_b128 v[180:183], v153 offset:2048
	ds_read_b128 v[184:187], v153 offset:3072
	s_add_u32 s36, s28, s34
	s_addc_u32 s37, s29, s35
	s_add_u32 s38, s36, 0x100
	s_addc_u32 s39, s37, 0
	s_add_u32 s66, s63, s34
	s_addc_u32 s67, s64, s35
	s_cmp_eq_u32 s34, 0
	s_cselect_b64 s[36:37], -1, 0
	s_and_b64 s[36:37], s[30:31], s[36:37]
	s_cmpk_eq_i32 s34, 0xf00
	v_cndmask_b32_e64 v188, 0, 1, s[36:37]
	s_cselect_b32 s39, s21, s39
	s_cselect_b32 s38, s61, s38
	v_readfirstlane_b32 s68, v188
	s_cselect_b32 s37, s19, s67
	s_cselect_b32 s36, s62, s66
	v_lshl_add_u64 v[220:221], v[148:149], 0, s[34:35]
	s_add_i32 m0, s27, 0xc000
	ds_read_b128 v[188:191], v155
	ds_read_b128 v[192:195], v155 offset:1024
	ds_read_b128 v[196:199], v155 offset:2048
	ds_read_b128 v[200:203], v155 offset:3072
	ds_read_b128 v[204:207], v155 offset:4096
	ds_read_b128 v[208:211], v155 offset:5120
	ds_read_b128 v[212:215], v155 offset:6144
	ds_read_b128 v[216:219], v155 offset:7168
	global_load_lds_dwordx4 v[220:221], off
	v_lshl_add_u64 v[220:221], v[146:147], 0, s[34:35]
	s_add_i32 m0, s27, 0xe000
	s_and_b32 s68, s68, 1
	global_load_lds_dwordx4 v[220:221], off
	s_cmp_lg_u32 s68, 0
	s_cbranch_scc1 .Lgk_rare_6
	s_waitcnt vmcnt(8)
.Lgk_back_6:
	s_waitcnt lgkmcnt(0)
	s_barrier
	s_setprio 1
	s_waitcnt lgkmcnt(0)
	v_mfma_f32_16x16x32_bf16 v[126:129], v[156:159], v[188:191], v[126:129]
	v_mfma_f32_16x16x32_bf16 v[122:125], v[164:167], v[188:191], v[122:125]
	v_mfma_f32_16x16x32_bf16 v[118:121], v[156:159], v[196:199], v[118:121]
	v_mfma_f32_16x16x32_bf16 v[110:113], v[164:167], v[196:199], v[110:113]
	v_mfma_f32_16x16x32_bf16 v[102:105], v[156:159], v[204:207], v[102:105]
	v_mfma_f32_16x16x32_bf16 v[94:97], v[164:167], v[204:207], v[94:97]
	v_mfma_f32_16x16x32_bf16 v[86:89], v[156:159], v[212:215], v[86:89]
	v_mfma_f32_16x16x32_bf16 v[78:81], v[164:167], v[212:215], v[78:81]
	v_mfma_f32_16x16x32_bf16 v[126:129], v[160:163], v[192:195], v[126:129]
	v_mfma_f32_16x16x32_bf16 v[122:125], v[168:171], v[192:195], v[122:125]
	v_mfma_f32_16x16x32_bf16 v[118:121], v[160:163], v[200:203], v[118:121]
	v_mfma_f32_16x16x32_bf16 v[110:113], v[168:171], v[200:203], v[110:113]
	v_mfma_f32_16x16x32_bf16 v[102:105], v[160:163], v[208:211], v[102:105]
	v_mfma_f32_16x16x32_bf16 v[94:97], v[168:171], v[208:211], v[94:97]
	v_mfma_f32_16x16x32_bf16 v[86:89], v[160:163], v[216:219], v[86:89]
	v_mfma_f32_16x16x32_bf16 v[78:81], v[168:171], v[216:219], v[78:81]
	s_setprio 0
	s_setprio 1
	v_mfma_f32_16x16x32_bf16 v[114:117], v[172:175], v[188:191], v[114:117]
	v_mfma_f32_16x16x32_bf16 v[106:109], v[180:183], v[188:191], v[106:109]
	v_mfma_f32_16x16x32_bf16 v[98:101], v[172:175], v[196:199], v[98:101]
	v_mfma_f32_16x16x32_bf16 v[90:93], v[180:183], v[196:199], v[90:93]
	v_mfma_f32_16x16x32_bf16 v[82:85], v[172:175], v[204:207], v[82:85]
	v_mfma_f32_16x16x32_bf16 v[74:77], v[180:183], v[204:207], v[74:77]
	v_mfma_f32_16x16x32_bf16 v[70:73], v[172:175], v[212:215], v[70:73]
	v_mfma_f32_16x16x32_bf16 v[66:69], v[180:183], v[212:215], v[66:69]
	v_mfma_f32_16x16x32_bf16 v[114:117], v[176:179], v[192:195], v[114:117]
	v_mfma_f32_16x16x32_bf16 v[106:109], v[184:187], v[192:195], v[106:109]
	v_mfma_f32_16x16x32_bf16 v[98:101], v[176:179], v[200:203], v[98:101]
	v_mfma_f32_16x16x32_bf16 v[90:93], v[184:187], v[200:203], v[90:93]
	v_mfma_f32_16x16x32_bf16 v[82:85], v[176:179], v[208:211], v[82:85]
	v_mfma_f32_16x16x32_bf16 v[74:77], v[184:187], v[208:211], v[74:77]
	v_mfma_f32_16x16x32_bf16 v[70:73], v[176:179], v[216:219], v[70:73]
	v_mfma_f32_16x16x32_bf16 v[66:69], v[184:187], v[216:219], v[66:69]
	s_setprio 0
	s_barrier
	s_add_i32 s66, s53, s45
	v_lshl_add_u64 v[220:221], s[36:37], 0, v[132:133]
	s_mov_b32 m0, s66
	ds_read_b128 v[188:191], v155 offset:16384
	ds_read_b128 v[192:195], v155 offset:17408
	ds_read_b128 v[196:199], v155 offset:18432
	ds_read_b128 v[200:203], v155 offset:19456
	ds_read_b128 v[204:207], v155 offset:20480
	ds_read_b128 v[208:211], v155 offset:21504
	ds_read_b128 v[212:215], v155 offset:22528
	ds_read_b128 v[216:219], v155 offset:23552
	global_load_lds_dwordx4 v[220:221], off
	s_add_i32 m0, s66, 0x2000
	s_add_u32 s66, s36, 0x80000
	v_lshl_add_u64 v[222:223], s[36:37], 0, v[136:137]
	s_addc_u32 s67, s37, 0
	s_add_i32 s69, s54, s45
	global_load_lds_dwordx4 v[222:223], off
	v_lshl_add_u64 v[224:225], s[66:67], 0, v[132:133]
	s_mov_b32 m0, s69
	v_lshl_add_u64 v[226:227], s[38:39], 0, v[134:135]
	global_load_lds_dwordx4 v[224:225], off
	v_lshl_add_u64 v[224:225], s[66:67], 0, v[136:137]
	s_add_i32 m0, s69, 0x2000
	s_nop 0
	global_load_lds_dwordx4 v[224:225], off
	v_lshl_add_u64 v[224:225], s[38:39], 0, v[130:131]
	s_mov_b32 m0, s27
	s_nop 0
	global_load_lds_dwordx4 v[224:225], off
	s_mov_b32 m0, s46
	s_nop 0
	global_load_lds_dwordx4 v[226:227], off
	s_cmp_lg_u32 s68, 0
	s_cbranch_scc1 .Lgk_rare_7
	s_waitcnt vmcnt(8)
.Lgk_back_7:
	s_waitcnt lgkmcnt(0)
	s_barrier
	s_setprio 1
	s_waitcnt lgkmcnt(0)
	v_mfma_f32_16x16x32_bf16 v[62:65], v[156:159], v[188:191], v[62:65]
	v_mfma_f32_16x16x32_bf16 v[58:61], v[164:167], v[188:191], v[58:61]
	v_mfma_f32_16x16x32_bf16 v[54:57], v[156:159], v[196:199], v[54:57]
	v_mfma_f32_16x16x32_bf16 v[46:49], v[164:167], v[196:199], v[46:49]
	v_mfma_f32_16x16x32_bf16 v[38:41], v[156:159], v[204:207], v[38:41]
	v_mfma_f32_16x16x32_bf16 v[30:33], v[164:167], v[204:207], v[30:33]
	v_mfma_f32_16x16x32_bf16 v[22:25], v[156:159], v[212:215], v[22:25]
	v_mfma_f32_16x16x32_bf16 v[14:17], v[164:167], v[212:215], v[14:17]
	v_mfma_f32_16x16x32_bf16 v[62:65], v[160:163], v[192:195], v[62:65]
	v_mfma_f32_16x16x32_bf16 v[58:61], v[168:171], v[192:195], v[58:61]
	v_mfma_f32_16x16x32_bf16 v[54:57], v[160:163], v[200:203], v[54:57]
	v_mfma_f32_16x16x32_bf16 v[46:49], v[168:171], v[200:203], v[46:49]
	v_mfma_f32_16x16x32_bf16 v[38:41], v[160:163], v[208:211], v[38:41]
	v_mfma_f32_16x16x32_bf16 v[30:33], v[168:171], v[208:211], v[30:33]
	v_mfma_f32_16x16x32_bf16 v[22:25], v[160:163], v[216:219], v[22:25]
	v_mfma_f32_16x16x32_bf16 v[14:17], v[168:171], v[216:219], v[14:17]
	s_setprio 0
	s_setprio 1
	v_mfma_f32_16x16x32_bf16 v[50:53], v[172:175], v[188:191], v[50:53]
	v_mfma_f32_16x16x32_bf16 v[42:45], v[180:183], v[188:191], v[42:45]
	v_mfma_f32_16x16x32_bf16 v[34:37], v[172:175], v[196:199], v[34:37]
	v_mfma_f32_16x16x32_bf16 v[26:29], v[180:183], v[196:199], v[26:29]
	v_mfma_f32_16x16x32_bf16 v[18:21], v[172:175], v[204:207], v[18:21]
	v_mfma_f32_16x16x32_bf16 v[10:13], v[180:183], v[204:207], v[10:13]
	v_mfma_f32_16x16x32_bf16 v[6:9], v[172:175], v[212:215], v[6:9]
	v_mfma_f32_16x16x32_bf16 v[2:5], v[180:183], v[212:215], v[2:5]
	v_mfma_f32_16x16x32_bf16 v[50:53], v[176:179], v[192:195], v[50:53]
	v_mfma_f32_16x16x32_bf16 v[42:45], v[184:187], v[192:195], v[42:45]
	v_mfma_f32_16x16x32_bf16 v[34:37], v[176:179], v[200:203], v[34:37]
	v_mfma_f32_16x16x32_bf16 v[26:29], v[184:187], v[200:203], v[26:29]
	v_mfma_f32_16x16x32_bf16 v[18:21], v[176:179], v[208:211], v[18:21]
	v_mfma_f32_16x16x32_bf16 v[10:13], v[184:187], v[208:211], v[10:13]
	v_mfma_f32_16x16x32_bf16 v[6:9], v[176:179], v[216:219], v[6:9]
	v_mfma_f32_16x16x32_bf16 v[2:5], v[184:187], v[216:219], v[2:5]
	s_setprio 0
	s_barrier
	s_add_i32 s66, 0, 0x18000
	s_add_i32 s67, 0, 0x1c000
	v_add_u32_e32 v168, s66, v150
	v_add_u32_e32 v184, s67, v150
	ds_read_b128 v[156:159], v168
	ds_read_b128 v[160:163], v168 offset:1024
	ds_read_b128 v[164:167], v168 offset:2048
	ds_read_b128 v[168:171], v168 offset:3072
	ds_read_b128 v[172:175], v184
	ds_read_b128 v[176:179], v184 offset:1024
	ds_read_b128 v[180:183], v184 offset:2048
	ds_read_b128 v[184:187], v184 offset:3072
	s_add_u32 s38, s38, 0x80000
	s_addc_u32 s39, s39, 0
	s_mov_b32 m0, s47
	v_lshl_add_u64 v[228:229], s[38:39], 0, v[130:131]
	ds_read_b128 v[188:191], v155 offset:32768
	ds_read_b128 v[192:195], v155 offset:33792
	ds_read_b128 v[196:199], v155 offset:34816
	ds_read_b128 v[200:203], v155 offset:35840
	ds_read_b128 v[204:207], v155 offset:36864
	ds_read_b128 v[208:211], v155 offset:37888
	ds_read_b128 v[212:215], v155 offset:38912
	ds_read_b128 v[216:219], v155 offset:39936
	global_load_lds_dwordx4 v[228:229], off
	v_lshl_add_u64 v[228:229], s[38:39], 0, v[134:135]
	s_mov_b32 m0, s48
	s_nop 0
	global_load_lds_dwordx4 v[228:229], off
	s_waitcnt vmcnt(8)
	s_waitcnt lgkmcnt(0)
	s_barrier
	s_setprio 1
	s_waitcnt lgkmcnt(0)
	v_mfma_f32_16x16x32_bf16 v[126:129], v[156:159], v[188:191], v[126:129]
	v_mfma_f32_16x16x32_bf16 v[122:125], v[164:167], v[188:191], v[122:125]
	v_mfma_f32_16x16x32_bf16 v[118:121], v[156:159], v[196:199], v[118:121]
	v_mfma_f32_16x16x32_bf16 v[110:113], v[164:167], v[196:199], v[110:113]
	v_mfma_f32_16x16x32_bf16 v[102:105], v[156:159], v[204:207], v[102:105]
	v_mfma_f32_16x16x32_bf16 v[94:97], v[164:167], v[204:207], v[94:97]
	v_mfma_f32_16x16x32_bf16 v[86:89], v[156:159], v[212:215], v[86:89]
	v_mfma_f32_16x16x32_bf16 v[78:81], v[164:167], v[212:215], v[78:81]
	v_mfma_f32_16x16x32_bf16 v[126:129], v[160:163], v[192:195], v[126:129]
	v_mfma_f32_16x16x32_bf16 v[122:125], v[168:171], v[192:195], v[122:125]
	v_mfma_f32_16x16x32_bf16 v[118:121], v[160:163], v[200:203], v[118:121]
	v_mfma_f32_16x16x32_bf16 v[110:113], v[168:171], v[200:203], v[110:113]
	v_mfma_f32_16x16x32_bf16 v[102:105], v[160:163], v[208:211], v[102:105]
	v_mfma_f32_16x16x32_bf16 v[94:97], v[168:171], v[208:211], v[94:97]
	v_mfma_f32_16x16x32_bf16 v[86:89], v[160:163], v[216:219], v[86:89]
	v_mfma_f32_16x16x32_bf16 v[78:81], v[168:171], v[216:219], v[78:81]
	s_setprio 0
	s_setprio 1
	v_mfma_f32_16x16x32_bf16 v[114:117], v[172:175], v[188:191], v[114:117]
	v_mfma_f32_16x16x32_bf16 v[106:109], v[180:183], v[188:191], v[106:109]
	v_mfma_f32_16x16x32_bf16 v[98:101], v[172:175], v[196:199], v[98:101]
	v_mfma_f32_16x16x32_bf16 v[90:93], v[180:183], v[196:199], v[90:93]
	v_mfma_f32_16x16x32_bf16 v[82:85], v[172:175], v[204:207], v[82:85]
	v_mfma_f32_16x16x32_bf16 v[74:77], v[180:183], v[204:207], v[74:77]
	v_mfma_f32_16x16x32_bf16 v[70:73], v[172:175], v[212:215], v[70:73]
	v_mfma_f32_16x16x32_bf16 v[66:69], v[180:183], v[212:215], v[66:69]
	v_mfma_f32_16x16x32_bf16 v[114:117], v[176:179], v[192:195], v[114:117]
	v_mfma_f32_16x16x32_bf16 v[106:109], v[184:187], v[192:195], v[106:109]
	v_mfma_f32_16x16x32_bf16 v[98:101], v[176:179], v[200:203], v[98:101]
	v_mfma_f32_16x16x32_bf16 v[90:93], v[184:187], v[200:203], v[90:93]
	v_mfma_f32_16x16x32_bf16 v[82:85], v[176:179], v[208:211], v[82:85]
	v_mfma_f32_16x16x32_bf16 v[74:77], v[184:187], v[208:211], v[74:77]
	v_mfma_f32_16x16x32_bf16 v[70:73], v[176:179], v[216:219], v[70:73]
	v_mfma_f32_16x16x32_bf16 v[66:69], v[184:187], v[216:219], v[66:69]
	s_setprio 0
	s_barrier
	s_add_i32 s38, s66, s45
	v_lshl_add_u64 v[220:221], v[220:221], 0, s[8:9]
	s_mov_b32 m0, s38
	ds_read_b128 v[188:191], v155 offset:49152
	ds_read_b128 v[192:195], v155 offset:50176
	ds_read_b128 v[196:199], v155 offset:51200
	ds_read_b128 v[200:203], v155 offset:52224
	ds_read_b128 v[204:207], v155 offset:53248
	ds_read_b128 v[208:211], v155 offset:54272
	ds_read_b128 v[212:215], v155 offset:55296
	ds_read_b128 v[216:219], v155 offset:56320
	global_load_lds_dwordx4 v[220:221], off
	s_add_i32 m0, s38, 0x2000
	s_add_u32 s36, s36, 0x80080
	v_lshl_add_u64 v[220:221], v[222:223], 0, s[8:9]
	s_addc_u32 s37, s37, 0
	s_add_i32 s38, s67, s45
	global_load_lds_dwordx4 v[220:221], off
	v_lshl_add_u64 v[220:221], s[36:37], 0, v[132:133]
	s_mov_b32 m0, s38
	s_nop 0
	global_load_lds_dwordx4 v[220:221], off
	v_lshl_add_u64 v[220:221], s[36:37], 0, v[136:137]
	s_add_i32 m0, s38, 0x2000
	s_nop 0
	global_load_lds_dwordx4 v[220:221], off
	v_lshl_add_u64 v[220:221], v[224:225], 0, s[8:9]
	s_mov_b32 m0, s49
	s_nop 0
	global_load_lds_dwordx4 v[220:221], off
	v_lshl_add_u64 v[220:221], v[226:227], 0, s[8:9]
	s_mov_b32 m0, s50
	s_nop 0
	global_load_lds_dwordx4 v[220:221], off
	s_waitcnt vmcnt(8)
	s_waitcnt lgkmcnt(0)
	s_barrier
	s_setprio 1
	s_waitcnt lgkmcnt(0)
	v_mfma_f32_16x16x32_bf16 v[62:65], v[156:159], v[188:191], v[62:65]
	v_mfma_f32_16x16x32_bf16 v[58:61], v[164:167], v[188:191], v[58:61]
	v_mfma_f32_16x16x32_bf16 v[54:57], v[156:159], v[196:199], v[54:57]
	v_mfma_f32_16x16x32_bf16 v[46:49], v[164:167], v[196:199], v[46:49]
	v_mfma_f32_16x16x32_bf16 v[38:41], v[156:159], v[204:207], v[38:41]
	v_mfma_f32_16x16x32_bf16 v[30:33], v[164:167], v[204:207], v[30:33]
	v_mfma_f32_16x16x32_bf16 v[22:25], v[156:159], v[212:215], v[22:25]
	v_mfma_f32_16x16x32_bf16 v[14:17], v[164:167], v[212:215], v[14:17]
	v_mfma_f32_16x16x32_bf16 v[62:65], v[160:163], v[192:195], v[62:65]
	v_mfma_f32_16x16x32_bf16 v[58:61], v[168:171], v[192:195], v[58:61]
	v_mfma_f32_16x16x32_bf16 v[54:57], v[160:163], v[200:203], v[54:57]
	v_mfma_f32_16x16x32_bf16 v[46:49], v[168:171], v[200:203], v[46:49]
	v_mfma_f32_16x16x32_bf16 v[38:41], v[160:163], v[208:211], v[38:41]
	v_mfma_f32_16x16x32_bf16 v[30:33], v[168:171], v[208:211], v[30:33]
	v_mfma_f32_16x16x32_bf16 v[22:25], v[160:163], v[216:219], v[22:25]
	v_mfma_f32_16x16x32_bf16 v[14:17], v[168:171], v[216:219], v[14:17]
	s_setprio 0
	s_setprio 1
	v_mfma_f32_16x16x32_bf16 v[50:53], v[172:175], v[188:191], v[50:53]
	v_mfma_f32_16x16x32_bf16 v[42:45], v[180:183], v[188:191], v[42:45]
	v_mfma_f32_16x16x32_bf16 v[34:37], v[172:175], v[196:199], v[34:37]
	v_mfma_f32_16x16x32_bf16 v[26:29], v[180:183], v[196:199], v[26:29]
	v_mfma_f32_16x16x32_bf16 v[18:21], v[172:175], v[204:207], v[18:21]
	v_mfma_f32_16x16x32_bf16 v[10:13], v[180:183], v[204:207], v[10:13]
	v_mfma_f32_16x16x32_bf16 v[6:9], v[172:175], v[212:215], v[6:9]
	v_mfma_f32_16x16x32_bf16 v[2:5], v[180:183], v[212:215], v[2:5]
	v_mfma_f32_16x16x32_bf16 v[50:53], v[176:179], v[192:195], v[50:53]
	v_mfma_f32_16x16x32_bf16 v[42:45], v[184:187], v[192:195], v[42:45]
	v_mfma_f32_16x16x32_bf16 v[34:37], v[176:179], v[200:203], v[34:37]
	v_mfma_f32_16x16x32_bf16 v[26:29], v[184:187], v[200:203], v[26:29]
	v_mfma_f32_16x16x32_bf16 v[18:21], v[176:179], v[208:211], v[18:21]
	v_mfma_f32_16x16x32_bf16 v[10:13], v[184:187], v[208:211], v[10:13]
	v_mfma_f32_16x16x32_bf16 v[6:9], v[176:179], v[216:219], v[6:9]
	v_mfma_f32_16x16x32_bf16 v[2:5], v[184:187], v[216:219], v[2:5]
	s_setprio 0
	s_barrier
	s_add_i32 s65, s65, 2
	s_add_u32 s34, s34, 0x100
	s_addc_u32 s35, s35, 0
	s_cmp_gt_u32 s65, 29
	s_cbranch_scc0 .LBB0_1009
	s_branch .Lgk_skip_3

.Lgk_skip_3:
	s_and_b64 vcc, exec, s[10:11]
	s_cbranch_vccz .LBB0_1012
	s_barrier

.LBB0_1173:
	ds_read_b128 v[156:159], v152
	ds_read_b128 v[160:163], v152 offset:1024
	ds_read_b128 v[164:167], v152 offset:2048
	ds_read_b128 v[168:171], v152 offset:3072
	ds_read_b128 v[172:175], v153
	ds_read_b128 v[176:179], v153 offset:1024
	ds_read_b128 v[180:183], v153 offset:2048
	ds_read_b128 v[184:187], v153 offset:3072
	s_add_u32 s26, s20, s24
	s_addc_u32 s27, s21, s25
	s_add_u32 s28, s26, 0x100
	s_addc_u32 s29, s27, 0
	s_add_u32 s56, s53, s24
	s_addc_u32 s57, s54, s25
	s_cmp_eq_u32 s24, 0
	s_cselect_b64 s[26:27], -1, 0
	s_and_b64 s[26:27], s[22:23], s[26:27]
	s_cmpk_eq_i32 s24, 0xf00
	v_cndmask_b32_e64 v188, 0, 1, s[26:27]
	s_cselect_b32 s29, s13, s29
	s_cselect_b32 s28, s51, s28
	v_readfirstlane_b32 s58, v188
	s_cselect_b32 s27, s11, s57
	s_cselect_b32 s26, s52, s56
	v_lshl_add_u64 v[220:221], v[148:149], 0, s[24:25]
	s_add_i32 m0, s19, 0xc000
	ds_read_b128 v[188:191], v155
	ds_read_b128 v[192:195], v155 offset:1024
	ds_read_b128 v[196:199], v155 offset:2048
	ds_read_b128 v[200:203], v155 offset:3072
	ds_read_b128 v[204:207], v155 offset:4096
	ds_read_b128 v[208:211], v155 offset:5120
	ds_read_b128 v[212:215], v155 offset:6144
	ds_read_b128 v[216:219], v155 offset:7168
	global_load_lds_dwordx4 v[220:221], off
	v_lshl_add_u64 v[220:221], v[146:147], 0, s[24:25]
	s_add_i32 m0, s19, 0xe000
	s_and_b32 s58, s58, 1
	global_load_lds_dwordx4 v[220:221], off
	s_cmp_lg_u32 s58, 0
	s_cbranch_scc1 .Lgk_rare_8
	s_waitcnt vmcnt(8)
.Lgk_back_8:
	s_waitcnt lgkmcnt(0)
	s_barrier
	s_setprio 1
	s_waitcnt lgkmcnt(0)
	v_mfma_f32_16x16x32_bf16 v[126:129], v[156:159], v[188:191], v[126:129]
	v_mfma_f32_16x16x32_bf16 v[122:125], v[164:167], v[188:191], v[122:125]
	v_mfma_f32_16x16x32_bf16 v[118:121], v[156:159], v[196:199], v[118:121]
	v_mfma_f32_16x16x32_bf16 v[110:113], v[164:167], v[196:199], v[110:113]
	v_mfma_f32_16x16x32_bf16 v[102:105], v[156:159], v[204:207], v[102:105]
	v_mfma_f32_16x16x32_bf16 v[94:97], v[164:167], v[204:207], v[94:97]
	v_mfma_f32_16x16x32_bf16 v[86:89], v[156:159], v[212:215], v[86:89]
	v_mfma_f32_16x16x32_bf16 v[78:81], v[164:167], v[212:215], v[78:81]
	v_mfma_f32_16x16x32_bf16 v[126:129], v[160:163], v[192:195], v[126:129]
	v_mfma_f32_16x16x32_bf16 v[122:125], v[168:171], v[192:195], v[122:125]
	v_mfma_f32_16x16x32_bf16 v[118:121], v[160:163], v[200:203], v[118:121]
	v_mfma_f32_16x16x32_bf16 v[110:113], v[168:171], v[200:203], v[110:113]
	v_mfma_f32_16x16x32_bf16 v[102:105], v[160:163], v[208:211], v[102:105]
	v_mfma_f32_16x16x32_bf16 v[94:97], v[168:171], v[208:211], v[94:97]
	v_mfma_f32_16x16x32_bf16 v[86:89], v[160:163], v[216:219], v[86:89]
	v_mfma_f32_16x16x32_bf16 v[78:81], v[168:171], v[216:219], v[78:81]
	s_setprio 0
	s_setprio 1
	v_mfma_f32_16x16x32_bf16 v[114:117], v[172:175], v[188:191], v[114:117]
	v_mfma_f32_16x16x32_bf16 v[106:109], v[180:183], v[188:191], v[106:109]
	v_mfma_f32_16x16x32_bf16 v[98:101], v[172:175], v[196:199], v[98:101]
	v_mfma_f32_16x16x32_bf16 v[90:93], v[180:183], v[196:199], v[90:93]
	v_mfma_f32_16x16x32_bf16 v[82:85], v[172:175], v[204:207], v[82:85]
	v_mfma_f32_16x16x32_bf16 v[74:77], v[180:183], v[204:207], v[74:77]
	v_mfma_f32_16x16x32_bf16 v[70:73], v[172:175], v[212:215], v[70:73]
	v_mfma_f32_16x16x32_bf16 v[66:69], v[180:183], v[212:215], v[66:69]
	v_mfma_f32_16x16x32_bf16 v[114:117], v[176:179], v[192:195], v[114:117]
	v_mfma_f32_16x16x32_bf16 v[106:109], v[184:187], v[192:195], v[106:109]
	v_mfma_f32_16x16x32_bf16 v[98:101], v[176:179], v[200:203], v[98:101]
	v_mfma_f32_16x16x32_bf16 v[90:93], v[184:187], v[200:203], v[90:93]
	v_mfma_f32_16x16x32_bf16 v[82:85], v[176:179], v[208:211], v[82:85]
	v_mfma_f32_16x16x32_bf16 v[74:77], v[184:187], v[208:211], v[74:77]
	v_mfma_f32_16x16x32_bf16 v[70:73], v[176:179], v[216:219], v[70:73]
	v_mfma_f32_16x16x32_bf16 v[66:69], v[184:187], v[216:219], v[66:69]
	s_setprio 0
	s_barrier
	s_add_i32 s56, s46, s36
	v_lshl_add_u64 v[220:221], s[26:27], 0, v[134:135]
	s_mov_b32 m0, s56
	ds_read_b128 v[188:191], v155 offset:16384
	ds_read_b128 v[192:195], v155 offset:17408
	ds_read_b128 v[196:199], v155 offset:18432
	ds_read_b128 v[200:203], v155 offset:19456
	ds_read_b128 v[204:207], v155 offset:20480
	ds_read_b128 v[208:211], v155 offset:21504
	ds_read_b128 v[212:215], v155 offset:22528
	ds_read_b128 v[216:219], v155 offset:23552
	global_load_lds_dwordx4 v[220:221], off
	s_add_i32 m0, s56, 0x2000
	s_add_u32 s56, s26, 0x80000
	v_lshl_add_u64 v[222:223], s[26:27], 0, v[130:131]
	s_addc_u32 s57, s27, 0
	s_add_i32 s59, s47, s36
	global_load_lds_dwordx4 v[222:223], off
	v_lshl_add_u64 v[224:225], s[56:57], 0, v[134:135]
	s_mov_b32 m0, s59
	v_lshl_add_u64 v[226:227], s[28:29], 0, v[132:133]
	global_load_lds_dwordx4 v[224:225], off
	v_lshl_add_u64 v[224:225], s[56:57], 0, v[130:131]
	s_add_i32 m0, s59, 0x2000
	s_nop 0
	global_load_lds_dwordx4 v[224:225], off
	v_lshl_add_u64 v[224:225], s[28:29], 0, v[136:137]
	s_mov_b32 m0, s19
	s_nop 0
	global_load_lds_dwordx4 v[224:225], off
	s_mov_b32 m0, s39
	s_nop 0
	global_load_lds_dwordx4 v[226:227], off
	s_cmp_lg_u32 s58, 0
	s_cbranch_scc1 .Lgk_rare_9
	s_waitcnt vmcnt(8)
.Lgk_back_9:
	s_waitcnt lgkmcnt(0)
	s_barrier
	s_setprio 1
	s_waitcnt lgkmcnt(0)
	v_mfma_f32_16x16x32_bf16 v[62:65], v[156:159], v[188:191], v[62:65]
	v_mfma_f32_16x16x32_bf16 v[58:61], v[164:167], v[188:191], v[58:61]
	v_mfma_f32_16x16x32_bf16 v[54:57], v[156:159], v[196:199], v[54:57]
	v_mfma_f32_16x16x32_bf16 v[46:49], v[164:167], v[196:199], v[46:49]
	v_mfma_f32_16x16x32_bf16 v[38:41], v[156:159], v[204:207], v[38:41]
	v_mfma_f32_16x16x32_bf16 v[30:33], v[164:167], v[204:207], v[30:33]
	v_mfma_f32_16x16x32_bf16 v[22:25], v[156:159], v[212:215], v[22:25]
	v_mfma_f32_16x16x32_bf16 v[14:17], v[164:167], v[212:215], v[14:17]
	v_mfma_f32_16x16x32_bf16 v[62:65], v[160:163], v[192:195], v[62:65]
	v_mfma_f32_16x16x32_bf16 v[58:61], v[168:171], v[192:195], v[58:61]
	v_mfma_f32_16x16x32_bf16 v[54:57], v[160:163], v[200:203], v[54:57]
	v_mfma_f32_16x16x32_bf16 v[46:49], v[168:171], v[200:203], v[46:49]
	v_mfma_f32_16x16x32_bf16 v[38:41], v[160:163], v[208:211], v[38:41]
	v_mfma_f32_16x16x32_bf16 v[30:33], v[168:171], v[208:211], v[30:33]
	v_mfma_f32_16x16x32_bf16 v[22:25], v[160:163], v[216:219], v[22:25]
	v_mfma_f32_16x16x32_bf16 v[14:17], v[168:171], v[216:219], v[14:17]
	s_setprio 0
	s_setprio 1
	v_mfma_f32_16x16x32_bf16 v[50:53], v[172:175], v[188:191], v[50:53]
	v_mfma_f32_16x16x32_bf16 v[42:45], v[180:183], v[188:191], v[42:45]
	v_mfma_f32_16x16x32_bf16 v[34:37], v[172:175], v[196:199], v[34:37]
	v_mfma_f32_16x16x32_bf16 v[26:29], v[180:183], v[196:199], v[26:29]
	v_mfma_f32_16x16x32_bf16 v[18:21], v[172:175], v[204:207], v[18:21]
	v_mfma_f32_16x16x32_bf16 v[10:13], v[180:183], v[204:207], v[10:13]
	v_mfma_f32_16x16x32_bf16 v[6:9], v[172:175], v[212:215], v[6:9]
	v_mfma_f32_16x16x32_bf16 v[2:5], v[180:183], v[212:215], v[2:5]
	v_mfma_f32_16x16x32_bf16 v[50:53], v[176:179], v[192:195], v[50:53]
	v_mfma_f32_16x16x32_bf16 v[42:45], v[184:187], v[192:195], v[42:45]
	v_mfma_f32_16x16x32_bf16 v[34:37], v[176:179], v[200:203], v[34:37]
	v_mfma_f32_16x16x32_bf16 v[26:29], v[184:187], v[200:203], v[26:29]
	v_mfma_f32_16x16x32_bf16 v[18:21], v[176:179], v[208:211], v[18:21]
	v_mfma_f32_16x16x32_bf16 v[10:13], v[184:187], v[208:211], v[10:13]
	v_mfma_f32_16x16x32_bf16 v[6:9], v[176:179], v[216:219], v[6:9]
	v_mfma_f32_16x16x32_bf16 v[2:5], v[184:187], v[216:219], v[2:5]
	s_setprio 0
	s_barrier
	s_add_i32 s56, 0, 0x18000
	s_add_i32 s57, 0, 0x1c000
	v_add_u32_e32 v168, s56, v150
	v_add_u32_e32 v184, s57, v150
	ds_read_b128 v[156:159], v168
	ds_read_b128 v[160:163], v168 offset:1024
	ds_read_b128 v[164:167], v168 offset:2048
	ds_read_b128 v[168:171], v168 offset:3072
	ds_read_b128 v[172:175], v184
	ds_read_b128 v[176:179], v184 offset:1024
	ds_read_b128 v[180:183], v184 offset:2048
	ds_read_b128 v[184:187], v184 offset:3072
	s_add_u32 s28, s28, 0x80000
	s_addc_u32 s29, s29, 0
	s_mov_b32 m0, s40
	v_lshl_add_u64 v[228:229], s[28:29], 0, v[136:137]
	ds_read_b128 v[188:191], v155 offset:32768
	ds_read_b128 v[192:195], v155 offset:33792
	ds_read_b128 v[196:199], v155 offset:34816
	ds_read_b128 v[200:203], v155 offset:35840
	ds_read_b128 v[204:207], v155 offset:36864
	ds_read_b128 v[208:211], v155 offset:37888
	ds_read_b128 v[212:215], v155 offset:38912
	ds_read_b128 v[216:219], v155 offset:39936
	global_load_lds_dwordx4 v[228:229], off
	v_lshl_add_u64 v[228:229], s[28:29], 0, v[132:133]
	s_mov_b32 m0, s41
	s_nop 0
	global_load_lds_dwordx4 v[228:229], off
	s_waitcnt vmcnt(8)
	s_waitcnt lgkmcnt(0)
	s_barrier
	s_setprio 1
	s_waitcnt lgkmcnt(0)
	v_mfma_f32_16x16x32_bf16 v[126:129], v[156:159], v[188:191], v[126:129]
	v_mfma_f32_16x16x32_bf16 v[122:125], v[164:167], v[188:191], v[122:125]
	v_mfma_f32_16x16x32_bf16 v[118:121], v[156:159], v[196:199], v[118:121]
	v_mfma_f32_16x16x32_bf16 v[110:113], v[164:167], v[196:199], v[110:113]
	v_mfma_f32_16x16x32_bf16 v[102:105], v[156:159], v[204:207], v[102:105]
	v_mfma_f32_16x16x32_bf16 v[94:97], v[164:167], v[204:207], v[94:97]
	v_mfma_f32_16x16x32_bf16 v[86:89], v[156:159], v[212:215], v[86:89]
	v_mfma_f32_16x16x32_bf16 v[78:81], v[164:167], v[212:215], v[78:81]
	v_mfma_f32_16x16x32_bf16 v[126:129], v[160:163], v[192:195], v[126:129]
	v_mfma_f32_16x16x32_bf16 v[122:125], v[168:171], v[192:195], v[122:125]
	v_mfma_f32_16x16x32_bf16 v[118:121], v[160:163], v[200:203], v[118:121]
	v_mfma_f32_16x16x32_bf16 v[110:113], v[168:171], v[200:203], v[110:113]
	v_mfma_f32_16x16x32_bf16 v[102:105], v[160:163], v[208:211], v[102:105]
	v_mfma_f32_16x16x32_bf16 v[94:97], v[168:171], v[208:211], v[94:97]
	v_mfma_f32_16x16x32_bf16 v[86:89], v[160:163], v[216:219], v[86:89]
	v_mfma_f32_16x16x32_bf16 v[78:81], v[168:171], v[216:219], v[78:81]
	s_setprio 0
	s_setprio 1
	v_mfma_f32_16x16x32_bf16 v[114:117], v[172:175], v[188:191], v[114:117]
	v_mfma_f32_16x16x32_bf16 v[106:109], v[180:183], v[188:191], v[106:109]
	v_mfma_f32_16x16x32_bf16 v[98:101], v[172:175], v[196:199], v[98:101]
	v_mfma_f32_16x16x32_bf16 v[90:93], v[180:183], v[196:199], v[90:93]
	v_mfma_f32_16x16x32_bf16 v[82:85], v[172:175], v[204:207], v[82:85]
	v_mfma_f32_16x16x32_bf16 v[74:77], v[180:183], v[204:207], v[74:77]
	v_mfma_f32_16x16x32_bf16 v[70:73], v[172:175], v[212:215], v[70:73]
	v_mfma_f32_16x16x32_bf16 v[66:69], v[180:183], v[212:215], v[66:69]
	v_mfma_f32_16x16x32_bf16 v[114:117], v[176:179], v[192:195], v[114:117]
	v_mfma_f32_16x16x32_bf16 v[106:109], v[184:187], v[192:195], v[106:109]
	v_mfma_f32_16x16x32_bf16 v[98:101], v[176:179], v[200:203], v[98:101]
	v_mfma_f32_16x16x32_bf16 v[90:93], v[184:187], v[200:203], v[90:93]
	v_mfma_f32_16x16x32_bf16 v[82:85], v[176:179], v[208:211], v[82:85]
	v_mfma_f32_16x16x32_bf16 v[74:77], v[184:187], v[208:211], v[74:77]
	v_mfma_f32_16x16x32_bf16 v[70:73], v[176:179], v[216:219], v[70:73]
	v_mfma_f32_16x16x32_bf16 v[66:69], v[184:187], v[216:219], v[66:69]
	s_setprio 0
	s_barrier
	s_add_i32 s28, s56, s36
	v_lshl_add_u64 v[220:221], v[220:221], 0, s[6:7]
	s_mov_b32 m0, s28
	ds_read_b128 v[188:191], v155 offset:49152
	ds_read_b128 v[192:195], v155 offset:50176
	ds_read_b128 v[196:199], v155 offset:51200
	ds_read_b128 v[200:203], v155 offset:52224
	ds_read_b128 v[204:207], v155 offset:53248
	ds_read_b128 v[208:211], v155 offset:54272
	ds_read_b128 v[212:215], v155 offset:55296
	ds_read_b128 v[216:219], v155 offset:56320
	global_load_lds_dwordx4 v[220:221], off
	s_add_i32 m0, s28, 0x2000
	s_add_u32 s26, s26, 0x80080
	v_lshl_add_u64 v[220:221], v[222:223], 0, s[6:7]
	s_addc_u32 s27, s27, 0
	s_add_i32 s28, s57, s36
	global_load_lds_dwordx4 v[220:221], off
	v_lshl_add_u64 v[220:221], s[26:27], 0, v[134:135]
	s_mov_b32 m0, s28
	s_nop 0
	global_load_lds_dwordx4 v[220:221], off
	v_lshl_add_u64 v[220:221], s[26:27], 0, v[130:131]
	s_add_i32 m0, s28, 0x2000
	s_nop 0
	global_load_lds_dwordx4 v[220:221], off
	v_lshl_add_u64 v[220:221], v[224:225], 0, s[6:7]
	s_mov_b32 m0, s42
	s_nop 0
	global_load_lds_dwordx4 v[220:221], off
	v_lshl_add_u64 v[220:221], v[226:227], 0, s[6:7]
	s_mov_b32 m0, s43
	s_nop 0
	global_load_lds_dwordx4 v[220:221], off
	s_waitcnt vmcnt(8)
	s_waitcnt lgkmcnt(0)
	s_barrier
	s_setprio 1
	s_waitcnt lgkmcnt(0)
	v_mfma_f32_16x16x32_bf16 v[62:65], v[156:159], v[188:191], v[62:65]
	v_mfma_f32_16x16x32_bf16 v[58:61], v[164:167], v[188:191], v[58:61]
	v_mfma_f32_16x16x32_bf16 v[54:57], v[156:159], v[196:199], v[54:57]
	v_mfma_f32_16x16x32_bf16 v[46:49], v[164:167], v[196:199], v[46:49]
	v_mfma_f32_16x16x32_bf16 v[38:41], v[156:159], v[204:207], v[38:41]
	v_mfma_f32_16x16x32_bf16 v[30:33], v[164:167], v[204:207], v[30:33]
	v_mfma_f32_16x16x32_bf16 v[22:25], v[156:159], v[212:215], v[22:25]
	v_mfma_f32_16x16x32_bf16 v[14:17], v[164:167], v[212:215], v[14:17]
	v_mfma_f32_16x16x32_bf16 v[62:65], v[160:163], v[192:195], v[62:65]
	v_mfma_f32_16x16x32_bf16 v[58:61], v[168:171], v[192:195], v[58:61]
	v_mfma_f32_16x16x32_bf16 v[54:57], v[160:163], v[200:203], v[54:57]
	v_mfma_f32_16x16x32_bf16 v[46:49], v[168:171], v[200:203], v[46:49]
	v_mfma_f32_16x16x32_bf16 v[38:41], v[160:163], v[208:211], v[38:41]
	v_mfma_f32_16x16x32_bf16 v[30:33], v[168:171], v[208:211], v[30:33]
	v_mfma_f32_16x16x32_bf16 v[22:25], v[160:163], v[216:219], v[22:25]
	v_mfma_f32_16x16x32_bf16 v[14:17], v[168:171], v[216:219], v[14:17]
	s_setprio 0
	s_setprio 1
	v_mfma_f32_16x16x32_bf16 v[50:53], v[172:175], v[188:191], v[50:53]
	v_mfma_f32_16x16x32_bf16 v[42:45], v[180:183], v[188:191], v[42:45]
	v_mfma_f32_16x16x32_bf16 v[34:37], v[172:175], v[196:199], v[34:37]
	v_mfma_f32_16x16x32_bf16 v[26:29], v[180:183], v[196:199], v[26:29]
	v_mfma_f32_16x16x32_bf16 v[18:21], v[172:175], v[204:207], v[18:21]
	v_mfma_f32_16x16x32_bf16 v[10:13], v[180:183], v[204:207], v[10:13]
	v_mfma_f32_16x16x32_bf16 v[6:9], v[172:175], v[212:215], v[6:9]
	v_mfma_f32_16x16x32_bf16 v[2:5], v[180:183], v[212:215], v[2:5]
	v_mfma_f32_16x16x32_bf16 v[50:53], v[176:179], v[192:195], v[50:53]
	v_mfma_f32_16x16x32_bf16 v[42:45], v[184:187], v[192:195], v[42:45]
	v_mfma_f32_16x16x32_bf16 v[34:37], v[176:179], v[200:203], v[34:37]
	v_mfma_f32_16x16x32_bf16 v[26:29], v[184:187], v[200:203], v[26:29]
	v_mfma_f32_16x16x32_bf16 v[18:21], v[176:179], v[208:211], v[18:21]
	v_mfma_f32_16x16x32_bf16 v[10:13], v[184:187], v[208:211], v[10:13]
	v_mfma_f32_16x16x32_bf16 v[6:9], v[176:179], v[216:219], v[6:9]
	v_mfma_f32_16x16x32_bf16 v[2:5], v[184:187], v[216:219], v[2:5]
	s_setprio 0
	s_barrier
	s_add_i32 s55, s55, 2
	s_add_u32 s24, s24, 0x100
	s_addc_u32 s25, s25, 0
	s_cmp_gt_u32 s55, 29
	s_cbranch_scc0 .LBB0_1173
	s_branch .Lgk_skip_4

.Lgk_skip_4:
	s_and_b64 vcc, exec, s[8:9]
	s_cbranch_vccz .LBB0_1176
	s_barrier

.LBB0_1417:
	ds_read_b128 v[156:159], v152
	ds_read_b128 v[160:163], v152 offset:1024
	ds_read_b128 v[164:167], v152 offset:2048
	ds_read_b128 v[168:171], v152 offset:3072
	ds_read_b128 v[172:175], v153
	ds_read_b128 v[176:179], v153 offset:1024
	ds_read_b128 v[180:183], v153 offset:2048
	ds_read_b128 v[184:187], v153 offset:3072
	s_add_u32 s28, s22, s26
	s_addc_u32 s29, s23, s27
	s_add_u32 s30, s28, 0x100
	s_addc_u32 s31, s29, 0
	s_add_u32 s62, s59, s26
	s_addc_u32 s63, s60, s27
	s_cmp_eq_u32 s26, 0
	s_cselect_b64 s[28:29], -1, 0
	s_and_b64 s[28:29], s[24:25], s[28:29]
	s_cmpk_eq_i32 s26, 0x2b00
	v_cndmask_b32_e64 v188, 0, 1, s[28:29]
	s_cselect_b32 s31, s7, s31
	s_cselect_b32 s30, s6, s30
	v_readfirstlane_b32 s64, v188
	s_cselect_b32 s29, s21, s63
	s_cselect_b32 s28, s20, s62
	v_lshl_add_u64 v[220:221], v[148:149], 0, s[26:27]
	s_add_i32 m0, s40, 0xc000
	ds_read_b128 v[188:191], v155
	ds_read_b128 v[192:195], v155 offset:1024
	ds_read_b128 v[196:199], v155 offset:2048
	ds_read_b128 v[200:203], v155 offset:3072
	ds_read_b128 v[204:207], v155 offset:4096
	ds_read_b128 v[208:211], v155 offset:5120
	ds_read_b128 v[212:215], v155 offset:6144
	ds_read_b128 v[216:219], v155 offset:7168
	global_load_lds_dwordx4 v[220:221], off
	v_lshl_add_u64 v[220:221], v[146:147], 0, s[26:27]
	s_add_i32 m0, s40, 0xe000
	s_and_b32 s64, s64, 1
	global_load_lds_dwordx4 v[220:221], off
	s_cmp_lg_u32 s64, 0
	s_cbranch_scc1 .Lgk_rare_10
	s_waitcnt vmcnt(8)
.Lgk_back_10:
	s_waitcnt lgkmcnt(0)
	s_barrier
	s_setprio 1
	s_waitcnt lgkmcnt(0)
	v_mfma_f32_16x16x32_bf16 v[126:129], v[156:159], v[188:191], v[126:129]
	v_mfma_f32_16x16x32_bf16 v[122:125], v[164:167], v[188:191], v[122:125]
	v_mfma_f32_16x16x32_bf16 v[118:121], v[156:159], v[196:199], v[118:121]
	v_mfma_f32_16x16x32_bf16 v[110:113], v[164:167], v[196:199], v[110:113]
	v_mfma_f32_16x16x32_bf16 v[102:105], v[156:159], v[204:207], v[102:105]
	v_mfma_f32_16x16x32_bf16 v[94:97], v[164:167], v[204:207], v[94:97]
	v_mfma_f32_16x16x32_bf16 v[86:89], v[156:159], v[212:215], v[86:89]
	v_mfma_f32_16x16x32_bf16 v[78:81], v[164:167], v[212:215], v[78:81]
	v_mfma_f32_16x16x32_bf16 v[126:129], v[160:163], v[192:195], v[126:129]
	v_mfma_f32_16x16x32_bf16 v[122:125], v[168:171], v[192:195], v[122:125]
	v_mfma_f32_16x16x32_bf16 v[118:121], v[160:163], v[200:203], v[118:121]
	v_mfma_f32_16x16x32_bf16 v[110:113], v[168:171], v[200:203], v[110:113]
	v_mfma_f32_16x16x32_bf16 v[102:105], v[160:163], v[208:211], v[102:105]
	v_mfma_f32_16x16x32_bf16 v[94:97], v[168:171], v[208:211], v[94:97]
	v_mfma_f32_16x16x32_bf16 v[86:89], v[160:163], v[216:219], v[86:89]
	v_mfma_f32_16x16x32_bf16 v[78:81], v[168:171], v[216:219], v[78:81]
	s_setprio 0
	s_setprio 1
	v_mfma_f32_16x16x32_bf16 v[114:117], v[172:175], v[188:191], v[114:117]
	v_mfma_f32_16x16x32_bf16 v[106:109], v[180:183], v[188:191], v[106:109]
	v_mfma_f32_16x16x32_bf16 v[98:101], v[172:175], v[196:199], v[98:101]
	v_mfma_f32_16x16x32_bf16 v[90:93], v[180:183], v[196:199], v[90:93]
	v_mfma_f32_16x16x32_bf16 v[82:85], v[172:175], v[204:207], v[82:85]
	v_mfma_f32_16x16x32_bf16 v[74:77], v[180:183], v[204:207], v[74:77]
	v_mfma_f32_16x16x32_bf16 v[70:73], v[172:175], v[212:215], v[70:73]
	v_mfma_f32_16x16x32_bf16 v[66:69], v[180:183], v[212:215], v[66:69]
	v_mfma_f32_16x16x32_bf16 v[114:117], v[176:179], v[192:195], v[114:117]
	v_mfma_f32_16x16x32_bf16 v[106:109], v[184:187], v[192:195], v[106:109]
	v_mfma_f32_16x16x32_bf16 v[98:101], v[176:179], v[200:203], v[98:101]
	v_mfma_f32_16x16x32_bf16 v[90:93], v[184:187], v[200:203], v[90:93]
	v_mfma_f32_16x16x32_bf16 v[82:85], v[176:179], v[208:211], v[82:85]
	v_mfma_f32_16x16x32_bf16 v[74:77], v[184:187], v[208:211], v[74:77]
	v_mfma_f32_16x16x32_bf16 v[70:73], v[176:179], v[216:219], v[70:73]
	v_mfma_f32_16x16x32_bf16 v[66:69], v[184:187], v[216:219], v[66:69]
	s_setprio 0
	s_barrier
	s_add_i32 s62, s48, s39
	v_lshl_add_u64 v[220:221], s[28:29], 0, v[132:133]
	s_mov_b32 m0, s62
	ds_read_b128 v[188:191], v155 offset:16384
	ds_read_b128 v[192:195], v155 offset:17408
	ds_read_b128 v[196:199], v155 offset:18432
	ds_read_b128 v[200:203], v155 offset:19456
	ds_read_b128 v[204:207], v155 offset:20480
	ds_read_b128 v[208:211], v155 offset:21504
	ds_read_b128 v[212:215], v155 offset:22528
	ds_read_b128 v[216:219], v155 offset:23552
	global_load_lds_dwordx4 v[220:221], off
	s_add_i32 m0, s62, 0x2000
	s_add_u32 s62, s28, 0x160000
	v_lshl_add_u64 v[222:223], s[28:29], 0, v[136:137]
	s_addc_u32 s63, s29, 0
	s_add_i32 s65, s49, s39
	global_load_lds_dwordx4 v[222:223], off
	v_lshl_add_u64 v[224:225], s[62:63], 0, v[132:133]
	s_mov_b32 m0, s65
	v_lshl_add_u64 v[226:227], s[30:31], 0, v[134:135]
	global_load_lds_dwordx4 v[224:225], off
	v_lshl_add_u64 v[224:225], s[62:63], 0, v[136:137]
	s_add_i32 m0, s65, 0x2000
	s_nop 0
	global_load_lds_dwordx4 v[224:225], off
	v_lshl_add_u64 v[224:225], s[30:31], 0, v[130:131]
	s_mov_b32 m0, s40
	s_nop 0
	global_load_lds_dwordx4 v[224:225], off
	s_mov_b32 m0, s41
	s_nop 0
	global_load_lds_dwordx4 v[226:227], off
	s_cmp_lg_u32 s64, 0
	s_cbranch_scc1 .Lgk_rare_11
	s_waitcnt vmcnt(8)
.Lgk_back_11:
	s_waitcnt lgkmcnt(0)
	s_barrier
	s_setprio 1
	s_waitcnt lgkmcnt(0)
	v_mfma_f32_16x16x32_bf16 v[62:65], v[156:159], v[188:191], v[62:65]
	v_mfma_f32_16x16x32_bf16 v[58:61], v[164:167], v[188:191], v[58:61]
	v_mfma_f32_16x16x32_bf16 v[54:57], v[156:159], v[196:199], v[54:57]
	v_mfma_f32_16x16x32_bf16 v[46:49], v[164:167], v[196:199], v[46:49]
	v_mfma_f32_16x16x32_bf16 v[38:41], v[156:159], v[204:207], v[38:41]
	v_mfma_f32_16x16x32_bf16 v[30:33], v[164:167], v[204:207], v[30:33]
	v_mfma_f32_16x16x32_bf16 v[22:25], v[156:159], v[212:215], v[22:25]
	v_mfma_f32_16x16x32_bf16 v[14:17], v[164:167], v[212:215], v[14:17]
	v_mfma_f32_16x16x32_bf16 v[62:65], v[160:163], v[192:195], v[62:65]
	v_mfma_f32_16x16x32_bf16 v[58:61], v[168:171], v[192:195], v[58:61]
	v_mfma_f32_16x16x32_bf16 v[54:57], v[160:163], v[200:203], v[54:57]
	v_mfma_f32_16x16x32_bf16 v[46:49], v[168:171], v[200:203], v[46:49]
	v_mfma_f32_16x16x32_bf16 v[38:41], v[160:163], v[208:211], v[38:41]
	v_mfma_f32_16x16x32_bf16 v[30:33], v[168:171], v[208:211], v[30:33]
	v_mfma_f32_16x16x32_bf16 v[22:25], v[160:163], v[216:219], v[22:25]
	v_mfma_f32_16x16x32_bf16 v[14:17], v[168:171], v[216:219], v[14:17]
	s_setprio 0
	s_setprio 1
	v_mfma_f32_16x16x32_bf16 v[50:53], v[172:175], v[188:191], v[50:53]
	v_mfma_f32_16x16x32_bf16 v[42:45], v[180:183], v[188:191], v[42:45]
	v_mfma_f32_16x16x32_bf16 v[34:37], v[172:175], v[196:199], v[34:37]
	v_mfma_f32_16x16x32_bf16 v[26:29], v[180:183], v[196:199], v[26:29]
	v_mfma_f32_16x16x32_bf16 v[18:21], v[172:175], v[204:207], v[18:21]
	v_mfma_f32_16x16x32_bf16 v[10:13], v[180:183], v[204:207], v[10:13]
	v_mfma_f32_16x16x32_bf16 v[6:9], v[172:175], v[212:215], v[6:9]
	v_mfma_f32_16x16x32_bf16 v[2:5], v[180:183], v[212:215], v[2:5]
	v_mfma_f32_16x16x32_bf16 v[50:53], v[176:179], v[192:195], v[50:53]
	v_mfma_f32_16x16x32_bf16 v[42:45], v[184:187], v[192:195], v[42:45]
	v_mfma_f32_16x16x32_bf16 v[34:37], v[176:179], v[200:203], v[34:37]
	v_mfma_f32_16x16x32_bf16 v[26:29], v[184:187], v[200:203], v[26:29]
	v_mfma_f32_16x16x32_bf16 v[18:21], v[176:179], v[208:211], v[18:21]
	v_mfma_f32_16x16x32_bf16 v[10:13], v[184:187], v[208:211], v[10:13]
	v_mfma_f32_16x16x32_bf16 v[6:9], v[176:179], v[216:219], v[6:9]
	v_mfma_f32_16x16x32_bf16 v[2:5], v[184:187], v[216:219], v[2:5]
	s_setprio 0
	s_barrier
	s_add_i32 s62, 0, 0x18000
	s_add_i32 s63, 0, 0x1c000
	v_add_u32_e32 v168, s62, v150
	v_add_u32_e32 v184, s63, v150
	ds_read_b128 v[156:159], v168
	ds_read_b128 v[160:163], v168 offset:1024
	ds_read_b128 v[164:167], v168 offset:2048
	ds_read_b128 v[168:171], v168 offset:3072
	ds_read_b128 v[172:175], v184
	ds_read_b128 v[176:179], v184 offset:1024
	ds_read_b128 v[180:183], v184 offset:2048
	ds_read_b128 v[184:187], v184 offset:3072
	s_add_u32 s30, s30, 0x160000
	s_addc_u32 s31, s31, 0
	s_mov_b32 m0, s42
	v_lshl_add_u64 v[228:229], s[30:31], 0, v[130:131]
	ds_read_b128 v[188:191], v155 offset:32768
	ds_read_b128 v[192:195], v155 offset:33792
	ds_read_b128 v[196:199], v155 offset:34816
	ds_read_b128 v[200:203], v155 offset:35840
	ds_read_b128 v[204:207], v155 offset:36864
	ds_read_b128 v[208:211], v155 offset:37888
	ds_read_b128 v[212:215], v155 offset:38912
	ds_read_b128 v[216:219], v155 offset:39936
	global_load_lds_dwordx4 v[228:229], off
	v_lshl_add_u64 v[228:229], s[30:31], 0, v[134:135]
	s_mov_b32 m0, s43
	s_nop 0
	global_load_lds_dwordx4 v[228:229], off
	s_waitcnt vmcnt(8)
	s_waitcnt lgkmcnt(0)
	s_barrier
	s_setprio 1
	s_waitcnt lgkmcnt(0)
	v_mfma_f32_16x16x32_bf16 v[126:129], v[156:159], v[188:191], v[126:129]
	v_mfma_f32_16x16x32_bf16 v[122:125], v[164:167], v[188:191], v[122:125]
	v_mfma_f32_16x16x32_bf16 v[118:121], v[156:159], v[196:199], v[118:121]
	v_mfma_f32_16x16x32_bf16 v[110:113], v[164:167], v[196:199], v[110:113]
	v_mfma_f32_16x16x32_bf16 v[102:105], v[156:159], v[204:207], v[102:105]
	v_mfma_f32_16x16x32_bf16 v[94:97], v[164:167], v[204:207], v[94:97]
	v_mfma_f32_16x16x32_bf16 v[86:89], v[156:159], v[212:215], v[86:89]
	v_mfma_f32_16x16x32_bf16 v[78:81], v[164:167], v[212:215], v[78:81]
	v_mfma_f32_16x16x32_bf16 v[126:129], v[160:163], v[192:195], v[126:129]
	v_mfma_f32_16x16x32_bf16 v[122:125], v[168:171], v[192:195], v[122:125]
	v_mfma_f32_16x16x32_bf16 v[118:121], v[160:163], v[200:203], v[118:121]
	v_mfma_f32_16x16x32_bf16 v[110:113], v[168:171], v[200:203], v[110:113]
	v_mfma_f32_16x16x32_bf16 v[102:105], v[160:163], v[208:211], v[102:105]
	v_mfma_f32_16x16x32_bf16 v[94:97], v[168:171], v[208:211], v[94:97]
	v_mfma_f32_16x16x32_bf16 v[86:89], v[160:163], v[216:219], v[86:89]
	v_mfma_f32_16x16x32_bf16 v[78:81], v[168:171], v[216:219], v[78:81]
	s_setprio 0
	s_setprio 1
	v_mfma_f32_16x16x32_bf16 v[114:117], v[172:175], v[188:191], v[114:117]
	v_mfma_f32_16x16x32_bf16 v[106:109], v[180:183], v[188:191], v[106:109]
	v_mfma_f32_16x16x32_bf16 v[98:101], v[172:175], v[196:199], v[98:101]
	v_mfma_f32_16x16x32_bf16 v[90:93], v[180:183], v[196:199], v[90:93]
	v_mfma_f32_16x16x32_bf16 v[82:85], v[172:175], v[204:207], v[82:85]
	v_mfma_f32_16x16x32_bf16 v[74:77], v[180:183], v[204:207], v[74:77]
	v_mfma_f32_16x16x32_bf16 v[70:73], v[172:175], v[212:215], v[70:73]
	v_mfma_f32_16x16x32_bf16 v[66:69], v[180:183], v[212:215], v[66:69]
	v_mfma_f32_16x16x32_bf16 v[114:117], v[176:179], v[192:195], v[114:117]
	v_mfma_f32_16x16x32_bf16 v[106:109], v[184:187], v[192:195], v[106:109]
	v_mfma_f32_16x16x32_bf16 v[98:101], v[176:179], v[200:203], v[98:101]
	v_mfma_f32_16x16x32_bf16 v[90:93], v[184:187], v[200:203], v[90:93]
	v_mfma_f32_16x16x32_bf16 v[82:85], v[176:179], v[208:211], v[82:85]
	v_mfma_f32_16x16x32_bf16 v[74:77], v[184:187], v[208:211], v[74:77]
	v_mfma_f32_16x16x32_bf16 v[70:73], v[176:179], v[216:219], v[70:73]
	v_mfma_f32_16x16x32_bf16 v[66:69], v[184:187], v[216:219], v[66:69]
	s_setprio 0
	s_barrier
	s_add_i32 s30, s62, s39
	v_lshl_add_u64 v[220:221], v[220:221], 0, s[8:9]
	s_mov_b32 m0, s30
	ds_read_b128 v[188:191], v155 offset:49152
	ds_read_b128 v[192:195], v155 offset:50176
	ds_read_b128 v[196:199], v155 offset:51200
	ds_read_b128 v[200:203], v155 offset:52224
	ds_read_b128 v[204:207], v155 offset:53248
	ds_read_b128 v[208:211], v155 offset:54272
	ds_read_b128 v[212:215], v155 offset:55296
	ds_read_b128 v[216:219], v155 offset:56320
	global_load_lds_dwordx4 v[220:221], off
	s_add_i32 m0, s30, 0x2000
	s_add_u32 s28, s28, 0x160080
	v_lshl_add_u64 v[220:221], v[222:223], 0, s[8:9]
	s_addc_u32 s29, s29, 0
	s_add_i32 s30, s63, s39
	global_load_lds_dwordx4 v[220:221], off
	v_lshl_add_u64 v[220:221], s[28:29], 0, v[132:133]
	s_mov_b32 m0, s30
	s_nop 0
	global_load_lds_dwordx4 v[220:221], off
	v_lshl_add_u64 v[220:221], s[28:29], 0, v[136:137]
	s_add_i32 m0, s30, 0x2000
	s_nop 0
	global_load_lds_dwordx4 v[220:221], off
	v_lshl_add_u64 v[220:221], v[224:225], 0, s[8:9]
	s_mov_b32 m0, s44
	s_nop 0
	global_load_lds_dwordx4 v[220:221], off
	v_lshl_add_u64 v[220:221], v[226:227], 0, s[8:9]
	s_mov_b32 m0, s45
	s_nop 0
	global_load_lds_dwordx4 v[220:221], off
	s_waitcnt vmcnt(8)
	s_waitcnt lgkmcnt(0)
	s_barrier
	s_setprio 1
	s_waitcnt lgkmcnt(0)
	v_mfma_f32_16x16x32_bf16 v[62:65], v[156:159], v[188:191], v[62:65]
	v_mfma_f32_16x16x32_bf16 v[58:61], v[164:167], v[188:191], v[58:61]
	v_mfma_f32_16x16x32_bf16 v[54:57], v[156:159], v[196:199], v[54:57]
	v_mfma_f32_16x16x32_bf16 v[46:49], v[164:167], v[196:199], v[46:49]
	v_mfma_f32_16x16x32_bf16 v[38:41], v[156:159], v[204:207], v[38:41]
	v_mfma_f32_16x16x32_bf16 v[30:33], v[164:167], v[204:207], v[30:33]
	v_mfma_f32_16x16x32_bf16 v[22:25], v[156:159], v[212:215], v[22:25]
	v_mfma_f32_16x16x32_bf16 v[14:17], v[164:167], v[212:215], v[14:17]
	v_mfma_f32_16x16x32_bf16 v[62:65], v[160:163], v[192:195], v[62:65]
	v_mfma_f32_16x16x32_bf16 v[58:61], v[168:171], v[192:195], v[58:61]
	v_mfma_f32_16x16x32_bf16 v[54:57], v[160:163], v[200:203], v[54:57]
	v_mfma_f32_16x16x32_bf16 v[46:49], v[168:171], v[200:203], v[46:49]
	v_mfma_f32_16x16x32_bf16 v[38:41], v[160:163], v[208:211], v[38:41]
	v_mfma_f32_16x16x32_bf16 v[30:33], v[168:171], v[208:211], v[30:33]
	v_mfma_f32_16x16x32_bf16 v[22:25], v[160:163], v[216:219], v[22:25]
	v_mfma_f32_16x16x32_bf16 v[14:17], v[168:171], v[216:219], v[14:17]
	s_setprio 0
	s_setprio 1
	v_mfma_f32_16x16x32_bf16 v[50:53], v[172:175], v[188:191], v[50:53]
	v_mfma_f32_16x16x32_bf16 v[42:45], v[180:183], v[188:191], v[42:45]
	v_mfma_f32_16x16x32_bf16 v[34:37], v[172:175], v[196:199], v[34:37]
	v_mfma_f32_16x16x32_bf16 v[26:29], v[180:183], v[196:199], v[26:29]
	v_mfma_f32_16x16x32_bf16 v[18:21], v[172:175], v[204:207], v[18:21]
	v_mfma_f32_16x16x32_bf16 v[10:13], v[180:183], v[204:207], v[10:13]
	v_mfma_f32_16x16x32_bf16 v[6:9], v[172:175], v[212:215], v[6:9]
	v_mfma_f32_16x16x32_bf16 v[2:5], v[180:183], v[212:215], v[2:5]
	v_mfma_f32_16x16x32_bf16 v[50:53], v[176:179], v[192:195], v[50:53]
	v_mfma_f32_16x16x32_bf16 v[42:45], v[184:187], v[192:195], v[42:45]
	v_mfma_f32_16x16x32_bf16 v[34:37], v[176:179], v[200:203], v[34:37]
	v_mfma_f32_16x16x32_bf16 v[26:29], v[184:187], v[200:203], v[26:29]
	v_mfma_f32_16x16x32_bf16 v[18:21], v[176:179], v[208:211], v[18:21]
	v_mfma_f32_16x16x32_bf16 v[10:13], v[184:187], v[208:211], v[10:13]
	v_mfma_f32_16x16x32_bf16 v[6:9], v[176:179], v[216:219], v[6:9]
	v_mfma_f32_16x16x32_bf16 v[2:5], v[184:187], v[216:219], v[2:5]
	s_setprio 0
	s_barrier
	s_add_i32 s61, s61, 2
	s_add_u32 s26, s26, 0x100
	s_addc_u32 s27, s27, 0
	s_cmpk_gt_u32 s61, 0x55
	s_cbranch_scc0 .LBB0_1417
	s_branch .Lgk_skip_5

.LBB0_1587:
	ds_read_b128 v[158:161], v153
	ds_read_b128 v[162:165], v153 offset:1024
	ds_read_b128 v[166:169], v153 offset:2048
	ds_read_b128 v[170:173], v153 offset:3072
	ds_read_b128 v[174:177], v155
	ds_read_b128 v[178:181], v155 offset:1024
	ds_read_b128 v[182:185], v155 offset:2048
	ds_read_b128 v[186:189], v155 offset:3072
	s_add_u32 s40, s30, s38
	s_addc_u32 s41, s31, s39
	s_add_u32 s42, s40, 0x100
	s_addc_u32 s43, s41, 0
	s_add_u32 s70, s25, s38
	s_addc_u32 s71, s27, s39
	s_cmp_eq_u32 s38, 0
	s_cselect_b64 s[40:41], -1, 0
	s_and_b64 s[40:41], s[36:37], s[40:41]
	s_cmpk_eq_i32 s38, 0xf00
	v_cndmask_b32_e64 v157, 0, 1, s[40:41]
	s_cselect_b32 s43, s7, s43
	s_cselect_b32 s42, s6, s42
	v_readfirstlane_b32 s72, v157
	s_cselect_b32 s41, s29, s71
	s_cselect_b32 s40, s28, s70
	v_lshl_add_u64 v[222:223], v[148:149], 0, s[38:39]
	s_add_i32 m0, s51, 0xc000
	ds_read_b128 v[190:193], v156
	ds_read_b128 v[194:197], v156 offset:1024
	ds_read_b128 v[198:201], v156 offset:2048
	ds_read_b128 v[202:205], v156 offset:3072
	ds_read_b128 v[206:209], v156 offset:4096
	ds_read_b128 v[210:213], v156 offset:5120
	ds_read_b128 v[214:217], v156 offset:6144
	ds_read_b128 v[218:221], v156 offset:7168
	global_load_lds_dwordx4 v[222:223], off
	v_lshl_add_u64 v[222:223], v[146:147], 0, s[38:39]
	s_add_i32 m0, s51, 0xe000
	s_and_b32 s72, s72, 1
	global_load_lds_dwordx4 v[222:223], off
	s_cmp_lg_u32 s72, 0
	s_cbranch_scc1 .Lgk_rare_12
	s_waitcnt vmcnt(8)
.Lgk_back_12:
	s_waitcnt lgkmcnt(0)
	s_barrier
	s_setprio 1
	s_waitcnt lgkmcnt(0)
	v_mfma_f32_16x16x32_bf16 v[126:129], v[158:161], v[190:193], v[126:129]
	v_mfma_f32_16x16x32_bf16 v[122:125], v[166:169], v[190:193], v[122:125]
	v_mfma_f32_16x16x32_bf16 v[118:121], v[158:161], v[198:201], v[118:121]
	v_mfma_f32_16x16x32_bf16 v[110:113], v[166:169], v[198:201], v[110:113]
	v_mfma_f32_16x16x32_bf16 v[102:105], v[158:161], v[206:209], v[102:105]
	v_mfma_f32_16x16x32_bf16 v[94:97], v[166:169], v[206:209], v[94:97]
	v_mfma_f32_16x16x32_bf16 v[86:89], v[158:161], v[214:217], v[86:89]
	v_mfma_f32_16x16x32_bf16 v[78:81], v[166:169], v[214:217], v[78:81]
	v_mfma_f32_16x16x32_bf16 v[126:129], v[162:165], v[194:197], v[126:129]
	v_mfma_f32_16x16x32_bf16 v[122:125], v[170:173], v[194:197], v[122:125]
	v_mfma_f32_16x16x32_bf16 v[118:121], v[162:165], v[202:205], v[118:121]
	v_mfma_f32_16x16x32_bf16 v[110:113], v[170:173], v[202:205], v[110:113]
	v_mfma_f32_16x16x32_bf16 v[102:105], v[162:165], v[210:213], v[102:105]
	v_mfma_f32_16x16x32_bf16 v[94:97], v[170:173], v[210:213], v[94:97]
	v_mfma_f32_16x16x32_bf16 v[86:89], v[162:165], v[218:221], v[86:89]
	v_mfma_f32_16x16x32_bf16 v[78:81], v[170:173], v[218:221], v[78:81]
	s_setprio 0
	s_setprio 1
	v_mfma_f32_16x16x32_bf16 v[114:117], v[174:177], v[190:193], v[114:117]
	v_mfma_f32_16x16x32_bf16 v[106:109], v[182:185], v[190:193], v[106:109]
	v_mfma_f32_16x16x32_bf16 v[98:101], v[174:177], v[198:201], v[98:101]
	v_mfma_f32_16x16x32_bf16 v[90:93], v[182:185], v[198:201], v[90:93]
	v_mfma_f32_16x16x32_bf16 v[82:85], v[174:177], v[206:209], v[82:85]
	v_mfma_f32_16x16x32_bf16 v[74:77], v[182:185], v[206:209], v[74:77]
	v_mfma_f32_16x16x32_bf16 v[70:73], v[174:177], v[214:217], v[70:73]
	v_mfma_f32_16x16x32_bf16 v[66:69], v[182:185], v[214:217], v[66:69]
	v_mfma_f32_16x16x32_bf16 v[114:117], v[178:181], v[194:197], v[114:117]
	v_mfma_f32_16x16x32_bf16 v[106:109], v[186:189], v[194:197], v[106:109]
	v_mfma_f32_16x16x32_bf16 v[98:101], v[178:181], v[202:205], v[98:101]
	v_mfma_f32_16x16x32_bf16 v[90:93], v[186:189], v[202:205], v[90:93]
	v_mfma_f32_16x16x32_bf16 v[82:85], v[178:181], v[210:213], v[82:85]
	v_mfma_f32_16x16x32_bf16 v[74:77], v[186:189], v[210:213], v[74:77]
	v_mfma_f32_16x16x32_bf16 v[70:73], v[178:181], v[218:221], v[70:73]
	v_mfma_f32_16x16x32_bf16 v[66:69], v[186:189], v[218:221], v[66:69]
	s_setprio 0
	s_barrier
	s_add_i32 s70, s60, s48
	v_lshl_add_u64 v[222:223], s[40:41], 0, v[134:135]
	s_mov_b32 m0, s70
	ds_read_b128 v[190:193], v156 offset:16384
	ds_read_b128 v[194:197], v156 offset:17408
	ds_read_b128 v[198:201], v156 offset:18432
	ds_read_b128 v[202:205], v156 offset:19456
	ds_read_b128 v[206:209], v156 offset:20480
	ds_read_b128 v[210:213], v156 offset:21504
	ds_read_b128 v[214:217], v156 offset:22528
	ds_read_b128 v[218:221], v156 offset:23552
	global_load_lds_dwordx4 v[222:223], off
	s_add_i32 m0, s70, 0x2000
	s_add_u32 s70, s40, 0x80000
	v_lshl_add_u64 v[224:225], s[40:41], 0, v[130:131]
	s_addc_u32 s71, s41, 0
	s_add_i32 s73, s61, s48
	global_load_lds_dwordx4 v[224:225], off
	v_lshl_add_u64 v[226:227], s[70:71], 0, v[134:135]
	s_mov_b32 m0, s73
	v_lshl_add_u64 v[228:229], s[42:43], 0, v[132:133]
	global_load_lds_dwordx4 v[226:227], off
	v_lshl_add_u64 v[226:227], s[70:71], 0, v[130:131]
	s_add_i32 m0, s73, 0x2000
	s_nop 0
	global_load_lds_dwordx4 v[226:227], off
	v_lshl_add_u64 v[226:227], s[42:43], 0, v[136:137]
	s_mov_b32 m0, s51
	s_nop 0
	global_load_lds_dwordx4 v[226:227], off
	s_mov_b32 m0, s52
	s_nop 0
	global_load_lds_dwordx4 v[228:229], off
	s_cmp_lg_u32 s72, 0
	s_cbranch_scc1 .Lgk_rare_13
	s_waitcnt vmcnt(8)
.Lgk_back_13:
	s_waitcnt lgkmcnt(0)
	s_barrier
	s_setprio 1
	s_waitcnt lgkmcnt(0)
	v_mfma_f32_16x16x32_bf16 v[62:65], v[158:161], v[190:193], v[62:65]
	v_mfma_f32_16x16x32_bf16 v[58:61], v[166:169], v[190:193], v[58:61]
	v_mfma_f32_16x16x32_bf16 v[54:57], v[158:161], v[198:201], v[54:57]
	v_mfma_f32_16x16x32_bf16 v[46:49], v[166:169], v[198:201], v[46:49]
	v_mfma_f32_16x16x32_bf16 v[38:41], v[158:161], v[206:209], v[38:41]
	v_mfma_f32_16x16x32_bf16 v[30:33], v[166:169], v[206:209], v[30:33]
	v_mfma_f32_16x16x32_bf16 v[22:25], v[158:161], v[214:217], v[22:25]
	v_mfma_f32_16x16x32_bf16 v[14:17], v[166:169], v[214:217], v[14:17]
	v_mfma_f32_16x16x32_bf16 v[62:65], v[162:165], v[194:197], v[62:65]
	v_mfma_f32_16x16x32_bf16 v[58:61], v[170:173], v[194:197], v[58:61]
	v_mfma_f32_16x16x32_bf16 v[54:57], v[162:165], v[202:205], v[54:57]
	v_mfma_f32_16x16x32_bf16 v[46:49], v[170:173], v[202:205], v[46:49]
	v_mfma_f32_16x16x32_bf16 v[38:41], v[162:165], v[210:213], v[38:41]
	v_mfma_f32_16x16x32_bf16 v[30:33], v[170:173], v[210:213], v[30:33]
	v_mfma_f32_16x16x32_bf16 v[22:25], v[162:165], v[218:221], v[22:25]
	v_mfma_f32_16x16x32_bf16 v[14:17], v[170:173], v[218:221], v[14:17]
	s_setprio 0
	s_setprio 1
	v_mfma_f32_16x16x32_bf16 v[50:53], v[174:177], v[190:193], v[50:53]
	v_mfma_f32_16x16x32_bf16 v[42:45], v[182:185], v[190:193], v[42:45]
	v_mfma_f32_16x16x32_bf16 v[34:37], v[174:177], v[198:201], v[34:37]
	v_mfma_f32_16x16x32_bf16 v[26:29], v[182:185], v[198:201], v[26:29]
	v_mfma_f32_16x16x32_bf16 v[18:21], v[174:177], v[206:209], v[18:21]
	v_mfma_f32_16x16x32_bf16 v[10:13], v[182:185], v[206:209], v[10:13]
	v_mfma_f32_16x16x32_bf16 v[6:9], v[174:177], v[214:217], v[6:9]
	v_mfma_f32_16x16x32_bf16 v[2:5], v[182:185], v[214:217], v[2:5]
	v_mfma_f32_16x16x32_bf16 v[50:53], v[178:181], v[194:197], v[50:53]
	v_mfma_f32_16x16x32_bf16 v[42:45], v[186:189], v[194:197], v[42:45]
	v_mfma_f32_16x16x32_bf16 v[34:37], v[178:181], v[202:205], v[34:37]
	v_mfma_f32_16x16x32_bf16 v[26:29], v[186:189], v[202:205], v[26:29]
	v_mfma_f32_16x16x32_bf16 v[18:21], v[178:181], v[210:213], v[18:21]
	v_mfma_f32_16x16x32_bf16 v[10:13], v[186:189], v[210:213], v[10:13]
	v_mfma_f32_16x16x32_bf16 v[6:9], v[178:181], v[218:221], v[6:9]
	v_mfma_f32_16x16x32_bf16 v[2:5], v[186:189], v[218:221], v[2:5]
	s_setprio 0
	s_barrier
	s_add_i32 s70, 0, 0x18000
	v_add_u32_e32 v157, s70, v150
	s_add_i32 s71, 0, 0x1c000
	ds_read_b128 v[158:161], v157
	ds_read_b128 v[162:165], v157 offset:1024
	ds_read_b128 v[166:169], v157 offset:2048
	ds_read_b128 v[170:173], v157 offset:3072
	v_add_u32_e32 v157, s71, v150
	ds_read_b128 v[174:177], v157
	ds_read_b128 v[178:181], v157 offset:1024
	ds_read_b128 v[182:185], v157 offset:2048
	ds_read_b128 v[186:189], v157 offset:3072
	s_add_u32 s42, s42, 0x80000
	s_addc_u32 s43, s43, 0
	s_mov_b32 m0, s53
	v_lshl_add_u64 v[230:231], s[42:43], 0, v[136:137]
	ds_read_b128 v[190:193], v156 offset:32768
	ds_read_b128 v[194:197], v156 offset:33792
	ds_read_b128 v[198:201], v156 offset:34816
	ds_read_b128 v[202:205], v156 offset:35840
	ds_read_b128 v[206:209], v156 offset:36864
	ds_read_b128 v[210:213], v156 offset:37888
	ds_read_b128 v[214:217], v156 offset:38912
	ds_read_b128 v[218:221], v156 offset:39936
	global_load_lds_dwordx4 v[230:231], off
	v_lshl_add_u64 v[230:231], s[42:43], 0, v[132:133]
	s_mov_b32 m0, s54
	s_nop 0
	global_load_lds_dwordx4 v[230:231], off
	s_waitcnt vmcnt(8)
	s_waitcnt lgkmcnt(0)
	s_barrier
	s_setprio 1
	s_waitcnt lgkmcnt(0)
	v_mfma_f32_16x16x32_bf16 v[126:129], v[158:161], v[190:193], v[126:129]
	v_mfma_f32_16x16x32_bf16 v[122:125], v[166:169], v[190:193], v[122:125]
	v_mfma_f32_16x16x32_bf16 v[118:121], v[158:161], v[198:201], v[118:121]
	v_mfma_f32_16x16x32_bf16 v[110:113], v[166:169], v[198:201], v[110:113]
	v_mfma_f32_16x16x32_bf16 v[102:105], v[158:161], v[206:209], v[102:105]
	v_mfma_f32_16x16x32_bf16 v[94:97], v[166:169], v[206:209], v[94:97]
	v_mfma_f32_16x16x32_bf16 v[86:89], v[158:161], v[214:217], v[86:89]
	v_mfma_f32_16x16x32_bf16 v[78:81], v[166:169], v[214:217], v[78:81]
	v_mfma_f32_16x16x32_bf16 v[126:129], v[162:165], v[194:197], v[126:129]
	v_mfma_f32_16x16x32_bf16 v[122:125], v[170:173], v[194:197], v[122:125]
	v_mfma_f32_16x16x32_bf16 v[118:121], v[162:165], v[202:205], v[118:121]
	v_mfma_f32_16x16x32_bf16 v[110:113], v[170:173], v[202:205], v[110:113]
	v_mfma_f32_16x16x32_bf16 v[102:105], v[162:165], v[210:213], v[102:105]
	v_mfma_f32_16x16x32_bf16 v[94:97], v[170:173], v[210:213], v[94:97]
	v_mfma_f32_16x16x32_bf16 v[86:89], v[162:165], v[218:221], v[86:89]
	v_mfma_f32_16x16x32_bf16 v[78:81], v[170:173], v[218:221], v[78:81]
	s_setprio 0
	s_setprio 1
	v_mfma_f32_16x16x32_bf16 v[114:117], v[174:177], v[190:193], v[114:117]
	v_mfma_f32_16x16x32_bf16 v[106:109], v[182:185], v[190:193], v[106:109]
	v_mfma_f32_16x16x32_bf16 v[98:101], v[174:177], v[198:201], v[98:101]
	v_mfma_f32_16x16x32_bf16 v[90:93], v[182:185], v[198:201], v[90:93]
	v_mfma_f32_16x16x32_bf16 v[82:85], v[174:177], v[206:209], v[82:85]
	v_mfma_f32_16x16x32_bf16 v[74:77], v[182:185], v[206:209], v[74:77]
	v_mfma_f32_16x16x32_bf16 v[70:73], v[174:177], v[214:217], v[70:73]
	v_mfma_f32_16x16x32_bf16 v[66:69], v[182:185], v[214:217], v[66:69]
	v_mfma_f32_16x16x32_bf16 v[114:117], v[178:181], v[194:197], v[114:117]
	v_mfma_f32_16x16x32_bf16 v[106:109], v[186:189], v[194:197], v[106:109]
	v_mfma_f32_16x16x32_bf16 v[98:101], v[178:181], v[202:205], v[98:101]
	v_mfma_f32_16x16x32_bf16 v[90:93], v[186:189], v[202:205], v[90:93]
	v_mfma_f32_16x16x32_bf16 v[82:85], v[178:181], v[210:213], v[82:85]
	v_mfma_f32_16x16x32_bf16 v[74:77], v[186:189], v[210:213], v[74:77]
	v_mfma_f32_16x16x32_bf16 v[70:73], v[178:181], v[218:221], v[70:73]
	v_mfma_f32_16x16x32_bf16 v[66:69], v[186:189], v[218:221], v[66:69]
	s_setprio 0
	s_barrier
	s_add_i32 s42, s70, s48
	v_lshl_add_u64 v[222:223], v[222:223], 0, s[12:13]
	s_mov_b32 m0, s42
	ds_read_b128 v[190:193], v156 offset:49152
	ds_read_b128 v[194:197], v156 offset:50176
	ds_read_b128 v[198:201], v156 offset:51200
	ds_read_b128 v[202:205], v156 offset:52224
	ds_read_b128 v[206:209], v156 offset:53248
	ds_read_b128 v[210:213], v156 offset:54272
	ds_read_b128 v[214:217], v156 offset:55296
	ds_read_b128 v[218:221], v156 offset:56320
	global_load_lds_dwordx4 v[222:223], off
	s_add_i32 m0, s42, 0x2000
	s_add_u32 s40, s40, 0x80080
	v_lshl_add_u64 v[222:223], v[224:225], 0, s[12:13]
	s_addc_u32 s41, s41, 0
	s_add_i32 s42, s71, s48
	global_load_lds_dwordx4 v[222:223], off
	v_lshl_add_u64 v[222:223], s[40:41], 0, v[134:135]
	s_mov_b32 m0, s42
	s_nop 0
	global_load_lds_dwordx4 v[222:223], off
	v_lshl_add_u64 v[222:223], s[40:41], 0, v[130:131]
	s_add_i32 m0, s42, 0x2000
	s_nop 0
	global_load_lds_dwordx4 v[222:223], off
	v_lshl_add_u64 v[222:223], v[226:227], 0, s[12:13]
	s_mov_b32 m0, s56
	s_nop 0
	global_load_lds_dwordx4 v[222:223], off
	v_lshl_add_u64 v[222:223], v[228:229], 0, s[12:13]
	s_mov_b32 m0, s57
	s_nop 0
	global_load_lds_dwordx4 v[222:223], off
	s_waitcnt vmcnt(8)
	s_waitcnt lgkmcnt(0)
	s_barrier
	s_setprio 1
	s_waitcnt lgkmcnt(0)
	v_mfma_f32_16x16x32_bf16 v[62:65], v[158:161], v[190:193], v[62:65]
	v_mfma_f32_16x16x32_bf16 v[58:61], v[166:169], v[190:193], v[58:61]
	v_mfma_f32_16x16x32_bf16 v[54:57], v[158:161], v[198:201], v[54:57]
	v_mfma_f32_16x16x32_bf16 v[46:49], v[166:169], v[198:201], v[46:49]
	v_mfma_f32_16x16x32_bf16 v[38:41], v[158:161], v[206:209], v[38:41]
	v_mfma_f32_16x16x32_bf16 v[30:33], v[166:169], v[206:209], v[30:33]
	v_mfma_f32_16x16x32_bf16 v[22:25], v[158:161], v[214:217], v[22:25]
	v_mfma_f32_16x16x32_bf16 v[14:17], v[166:169], v[214:217], v[14:17]
	v_mfma_f32_16x16x32_bf16 v[62:65], v[162:165], v[194:197], v[62:65]
	v_mfma_f32_16x16x32_bf16 v[58:61], v[170:173], v[194:197], v[58:61]
	v_mfma_f32_16x16x32_bf16 v[54:57], v[162:165], v[202:205], v[54:57]
	v_mfma_f32_16x16x32_bf16 v[46:49], v[170:173], v[202:205], v[46:49]
	v_mfma_f32_16x16x32_bf16 v[38:41], v[162:165], v[210:213], v[38:41]
	v_mfma_f32_16x16x32_bf16 v[30:33], v[170:173], v[210:213], v[30:33]
	v_mfma_f32_16x16x32_bf16 v[22:25], v[162:165], v[218:221], v[22:25]
	v_mfma_f32_16x16x32_bf16 v[14:17], v[170:173], v[218:221], v[14:17]
	s_setprio 0
	s_setprio 1
	v_mfma_f32_16x16x32_bf16 v[50:53], v[174:177], v[190:193], v[50:53]
	v_mfma_f32_16x16x32_bf16 v[42:45], v[182:185], v[190:193], v[42:45]
	v_mfma_f32_16x16x32_bf16 v[34:37], v[174:177], v[198:201], v[34:37]
	v_mfma_f32_16x16x32_bf16 v[26:29], v[182:185], v[198:201], v[26:29]
	v_mfma_f32_16x16x32_bf16 v[18:21], v[174:177], v[206:209], v[18:21]
	v_mfma_f32_16x16x32_bf16 v[10:13], v[182:185], v[206:209], v[10:13]
	v_mfma_f32_16x16x32_bf16 v[6:9], v[174:177], v[214:217], v[6:9]
	v_mfma_f32_16x16x32_bf16 v[2:5], v[182:185], v[214:217], v[2:5]
	v_mfma_f32_16x16x32_bf16 v[50:53], v[178:181], v[194:197], v[50:53]
	v_mfma_f32_16x16x32_bf16 v[42:45], v[186:189], v[194:197], v[42:45]
	v_mfma_f32_16x16x32_bf16 v[34:37], v[178:181], v[202:205], v[34:37]
	v_mfma_f32_16x16x32_bf16 v[26:29], v[186:189], v[202:205], v[26:29]
	v_mfma_f32_16x16x32_bf16 v[18:21], v[178:181], v[210:213], v[18:21]
	v_mfma_f32_16x16x32_bf16 v[10:13], v[186:189], v[210:213], v[10:13]
	v_mfma_f32_16x16x32_bf16 v[6:9], v[178:181], v[218:221], v[6:9]
	v_mfma_f32_16x16x32_bf16 v[2:5], v[186:189], v[218:221], v[2:5]
	s_setprio 0
	s_barrier
	s_add_i32 s69, s69, 2
	s_add_u32 s38, s38, 0x100
	s_addc_u32 s39, s39, 0
	s_cmp_gt_u32 s69, 29
	s_cbranch_scc0 .LBB0_1587
	s_branch .Lgk_skip_6
